# sample window-attention cache loads without nt: the 8 query heads of a kv head (8 waves of one workgroup) re-read the same cache lines
# speedup vs baseline: 1.0434x; 1.0047x over previous
.LBB0_532:
	s_ashr_i32 s44, s40, 4
	s_add_i32 s20, s44, 0x4000
	s_and_b32 s41, s40, 15
	s_ashr_i32 s21, s20, 31
	s_mul_i32 s23, s20, 0x1800
	s_mul_hi_i32 s22, s20, 0x1800
	s_add_u32 s23, s0, s23
	s_addc_u32 s24, s1, s22
	s_lshl_b32 s22, s41, 7
	s_add_u32 s22, s23, s22
	s_addc_u32 s23, s24, 0
	s_lshl_b64 s[30:31], s[20:21], 8
	s_add_u32 s21, s4, s30
	s_addc_u32 s24, s9, s31
	s_lshl_b32 s42, s40, 3
	s_and_b32 s45, s42, 64
	s_lshl_b32 s46, s45, 1
	s_add_u32 s42, s21, s46
	s_addc_u32 s43, s24, 0
	s_add_u32 s21, s14, s30
	s_addc_u32 s24, s28, s31
	s_add_u32 s30, s21, s46
	s_waitcnt vmcnt(24) lgkmcnt(2)
	v_lshl_add_u64 v[6:7], s[42:43], 0, v[104:105]
	s_addc_u32 s31, s24, 0
	s_add_i32 s24, s41, s29
	v_lshl_add_u64 v[4:5], s[22:23], 0, v[104:105]
	global_load_dwordx2 v[6:7], v[6:7], off
	s_nop 0
	global_load_dwordx2 v[106:107], v2, s[30:31]
	global_load_dwordx2 v[112:113], v[4:5], off
	s_lshl_b64 s[30:31], s[24:25], 2
	s_add_u32 s30, s2, s30
	s_addc_u32 s31, s3, s31
	global_load_dword v120, v3, s[30:31] offset:-128
	v_lshl_or_b32 v4, s44, 7, v197
	v_ashrrev_i32_e32 v5, 31, v4
	v_lshlrev_b64 v[110:111], 9, v[4:5]
	v_lshl_or_b32 v110, s45, 2, v110
	v_lshl_add_u64 v[4:5], v[100:101], 0, v[110:111]
	s_waitcnt vmcnt(3)
	v_lshlrev_b32_e32 v121, 16, v6
	v_and_b32_e32 v123, 0xffff0000, v6
	v_lshlrev_b32_e32 v122, 16, v7
	v_and_b32_e32 v124, 0xffff0000, v7
	v_add_co_u32_e32 v6, vcc, s17, v4
	global_load_dwordx4 v[126:129], v[4:5], off
	global_load_dwordx4 v[130:133], v[4:5], off offset:2048
	v_addc_co_u32_e32 v7, vcc, 0, v5, vcc
	v_add_co_u32_e32 v108, vcc, s91, v4
	s_movk_i32 s21, 0x6000
	s_nop 0
	v_addc_co_u32_e32 v109, vcc, 0, v5, vcc
	v_add_co_u32_e32 v8, vcc, s50, v4
	global_load_dwordx4 v[134:137], v[108:109], off
	global_load_dwordx4 v[138:141], v[108:109], off offset:2048
	v_addc_co_u32_e32 v9, vcc, 0, v5, vcc
	s_waitcnt lgkmcnt(1)
	v_add_co_u32_e32 v10, vcc, s90, v4
	s_waitcnt vmcnt(4)
	v_mul_f32_e32 v120, 0x3fb8aa3b, v120
	s_waitcnt lgkmcnt(0)
	v_addc_co_u32_e32 v11, vcc, 0, v5, vcc
	global_load_dwordx4 v[142:145], v[6:7], off offset:2048
	global_load_dwordx4 v[146:149], v[8:9], off offset:2048
	global_load_dwordx4 v[150:153], v[10:11], off offset:-4096
	global_load_dwordx4 v[96:99], v[10:11], off
	v_add_co_u32_e32 v6, vcc, s96, v4
	s_nop 1
	v_addc_co_u32_e32 v7, vcc, 0, v5, vcc
	v_add_co_u32_e32 v8, vcc, s21, v4
	s_nop 1
	v_addc_co_u32_e32 v9, vcc, 0, v5, vcc
	global_load_dwordx4 v[92:95], v[10:11], off offset:2048
	global_load_dwordx4 v[88:91], v[8:9], off offset:-4096
	global_load_dwordx4 v[80:83], v[8:9], off
	global_load_dwordx4 v[76:79], v[8:9], off offset:2048
	v_add_co_u32_e32 v8, vcc, s51, v4
	s_nop 1
	v_addc_co_u32_e32 v9, vcc, 0, v5, vcc
	v_add_co_u32_e32 v10, vcc, s92, v4
	s_nop 1
	v_addc_co_u32_e32 v11, vcc, 0, v5, vcc
	global_load_dwordx4 v[84:87], v[6:7], off offset:2048
	global_load_dwordx4 v[68:71], v[8:9], off offset:2048
	global_load_dwordx4 v[72:75], v[10:11], off offset:-4096
	global_load_dwordx4 v[64:67], v[10:11], off
	v_add_co_u32_e32 v6, vcc, s56, v4
	s_nop 1
	v_addc_co_u32_e32 v7, vcc, 0, v5, vcc
	v_add_co_u32_e32 v8, vcc, s93, v4
	s_nop 1
	v_addc_co_u32_e32 v9, vcc, 0, v5, vcc
	global_load_dwordx4 v[60:63], v[10:11], off offset:2048
	global_load_dwordx4 v[56:59], v[8:9], off offset:-4096
	global_load_dwordx4 v[48:51], v[8:9], off
	global_load_dwordx4 v[44:47], v[8:9], off offset:2048
	v_add_co_u32_e32 v8, vcc, s57, v4
	s_nop 1
	v_addc_co_u32_e32 v9, vcc, 0, v5, vcc
	v_add_co_u32_e32 v10, vcc, s6, v4
	s_nop 1
	v_addc_co_u32_e32 v11, vcc, 0, v5, vcc
	global_load_dwordx4 v[52:55], v[6:7], off offset:2048
	global_load_dwordx4 v[36:39], v[8:9], off offset:2048
	global_load_dwordx4 v[40:43], v[10:11], off offset:-4096
	global_load_dwordx4 v[32:35], v[10:11], off
	v_add_co_u32_e32 v6, vcc, s58, v4
	s_nop 1
	v_addc_co_u32_e32 v7, vcc, 0, v5, vcc
	v_add_co_u32_e32 v8, vcc, s95, v4
	s_nop 1
	v_addc_co_u32_e32 v9, vcc, 0, v5, vcc
	v_add_co_u32_e32 v4, vcc, s52, v4
	global_load_dwordx4 v[28:31], v[10:11], off offset:2048
	global_load_dwordx4 v[24:27], v[8:9], off offset:-4096
	global_load_dwordx4 v[16:19], v[8:9], off
	global_load_dwordx4 v[12:15], v[8:9], off offset:2048
	v_addc_co_u32_e32 v5, vcc, 0, v5, vcc
	global_load_dwordx4 v[20:23], v[6:7], off offset:2048
	global_load_dwordx4 v[8:11], v[4:5], off
	global_load_dwordx4 v[154:157], v[108:109], off offset:-4096
	s_nop 0
	global_load_dwordx4 v[4:7], v[4:5], off offset:2048
	v_and_b32_e32 v108, 0xffff0000, v112
	v_lshlrev_b32_e32 v109, 16, v113
	v_lshlrev_b32_e32 v112, 16, v112
	v_and_b32_e32 v113, 0xffff0000, v113
	s_waitcnt vmcnt(31)
	v_mov_b32_e32 v158, v127
	v_mov_b32_e32 v127, v129
	v_mov_b32_e32 v159, v128
	v_pk_mul_f32 v[126:127], v[126:127], v[112:113]
	s_movk_i32 s33, 0x6000
	v_pk_fma_f32 v[126:127], v[158:159], v[108:109], v[126:127]
	s_nop 0
	v_add_f32_e32 v125, v126, v127
	s_waitcnt vmcnt(30)
	v_mov_b32_e32 v126, v131
	v_mov_b32_e32 v131, v133
	v_mov_b32_e32 v127, v132
	v_pk_mul_f32 v[128:129], v[130:131], v[112:113]
	ds_bpermute_b32 v158, v114, v125
	v_pk_fma_f32 v[126:127], v[126:127], v[108:109], v[128:129]
	s_waitcnt lgkmcnt(0)
	v_add_f32_e32 v125, v125, v158
	v_add_f32_e32 v126, v126, v127
	ds_bpermute_b32 v127, v114, v126
	ds_bpermute_b32 v128, v115, v125
	s_waitcnt lgkmcnt(1)
	v_add_f32_e32 v126, v126, v127
	ds_bpermute_b32 v127, v115, v126
	s_waitcnt lgkmcnt(1)
	v_add_f32_e32 v125, v125, v128
	ds_bpermute_b32 v128, v116, v125
	s_waitcnt lgkmcnt(1)
	v_add_f32_e32 v126, v126, v127
	ds_bpermute_b32 v127, v116, v126
	s_waitcnt lgkmcnt(1)
	v_add_f32_e32 v125, v125, v128
	ds_bpermute_b32 v130, v117, v125
	s_waitcnt lgkmcnt(1)
	v_add_f32_e32 v131, v126, v127
	s_waitcnt vmcnt(1)
	v_mov_b32_e32 v126, v155
	v_mov_b32_e32 v155, v157
	v_mov_b32_e32 v127, v156
	v_pk_mul_f32 v[128:129], v[154:155], v[112:113]
	ds_bpermute_b32 v132, v117, v131
	v_pk_fma_f32 v[126:127], v[126:127], v[108:109], v[128:129]
	s_waitcnt lgkmcnt(1)
	v_add_f32_e32 v130, v125, v130
	v_add_f32_e32 v133, v126, v127
	v_mov_b32_e32 v126, v143
	v_mov_b32_e32 v143, v145
	v_mov_b32_e32 v127, v144
	v_pk_mul_f32 v[128:129], v[142:143], v[112:113]
	ds_bpermute_b32 v154, v114, v133
	v_pk_fma_f32 v[126:127], v[126:127], v[108:109], v[128:129]
	v_mov_b32_e32 v129, v136
	v_add_f32_e32 v127, v126, v127
	ds_bpermute_b32 v128, v114, v127
	s_waitcnt lgkmcnt(2)
	v_add_f32_e32 v126, v131, v132
	s_waitcnt lgkmcnt(1)
	v_add_f32_e32 v125, v133, v154
	ds_bpermute_b32 v131, v115, v125
	s_waitcnt lgkmcnt(1)
	v_add_f32_e32 v127, v127, v128
	v_mov_b32_e32 v128, v135
	v_mov_b32_e32 v135, v137
	v_pk_mul_f32 v[132:133], v[134:135], v[112:113]
	ds_bpermute_b32 v142, v115, v127
	v_pk_fma_f32 v[128:129], v[128:129], v[108:109], v[132:133]
	s_waitcnt lgkmcnt(1)
	v_add_f32_e32 v125, v125, v131
	v_add_f32_e32 v128, v128, v129
	ds_bpermute_b32 v129, v114, v128
	s_waitcnt lgkmcnt(1)
	v_add_f32_e32 v127, v127, v142
	ds_bpermute_b32 v132, v116, v127
	ds_bpermute_b32 v131, v116, v125
	s_waitcnt lgkmcnt(2)
	v_add_f32_e32 v128, v128, v129
	ds_bpermute_b32 v129, v115, v128
	s_waitcnt lgkmcnt(2)
	v_add_f32_e32 v127, v127, v132
	s_waitcnt lgkmcnt(1)
	v_add_f32_e32 v125, v125, v131
	ds_bpermute_b32 v131, v117, v125
	ds_bpermute_b32 v134, v117, v127
	s_waitcnt lgkmcnt(2)
	v_add_f32_e32 v135, v128, v129
	v_mov_b32_e32 v128, v139
	v_mov_b32_e32 v139, v141
	v_mov_b32_e32 v129, v140
	v_pk_mul_f32 v[132:133], v[138:139], v[112:113]
	ds_bpermute_b32 v136, v116, v135
	v_pk_fma_f32 v[128:129], v[128:129], v[108:109], v[132:133]
	v_mov_b32_e32 v133, v152
	v_add_f32_e32 v129, v128, v129
	ds_bpermute_b32 v132, v114, v129
	s_waitcnt lgkmcnt(3)
	v_add_f32_e32 v128, v125, v131
	s_waitcnt lgkmcnt(2)
	v_add_f32_e32 v125, v127, v134
	s_waitcnt lgkmcnt(1)
	v_add_f32_e32 v127, v135, v136
	ds_bpermute_b32 v131, v117, v127
	s_waitcnt lgkmcnt(1)
	v_add_f32_e32 v129, v129, v132
	v_mov_b32_e32 v132, v151
	v_mov_b32_e32 v151, v153
	v_pk_mul_f32 v[134:135], v[150:151], v[112:113]
	ds_bpermute_b32 v136, v115, v129
	v_pk_fma_f32 v[132:133], v[132:133], v[108:109], v[134:135]
	s_waitcnt lgkmcnt(0)
	v_add_f32_e32 v129, v129, v136
	v_add_f32_e32 v137, v132, v133
	v_mov_b32_e32 v132, v147
	v_mov_b32_e32 v147, v149
	v_mov_b32_e32 v133, v148
	v_pk_mul_f32 v[134:135], v[146:147], v[112:113]
	ds_bpermute_b32 v138, v114, v137
	v_pk_fma_f32 v[132:133], v[132:133], v[108:109], v[134:135]
	ds_bpermute_b32 v134, v116, v129
	v_add_f32_e32 v132, v132, v133
	ds_bpermute_b32 v133, v114, v132
	s_waitcnt lgkmcnt(2)
	v_add_f32_e32 v135, v137, v138
	ds_bpermute_b32 v136, v115, v135
	s_waitcnt lgkmcnt(2)
	v_add_f32_e32 v134, v129, v134
	v_add_f32_e32 v129, v127, v131
	s_waitcnt lgkmcnt(1)
	v_add_f32_e32 v132, v132, v133
	ds_bpermute_b32 v133, v115, v132
	s_waitcnt lgkmcnt(1)
	v_add_f32_e32 v135, v135, v136
	ds_bpermute_b32 v136, v116, v135
	ds_bpermute_b32 v137, v117, v134
	s_waitcnt lgkmcnt(2)
	v_add_f32_e32 v132, v132, v133
	ds_bpermute_b32 v133, v116, v132
	s_waitcnt lgkmcnt(2)
	v_add_f32_e32 v131, v135, v136
	s_waitcnt lgkmcnt(1)
	v_add_f32_e32 v127, v134, v137
	ds_bpermute_b32 v134, v117, v131
	s_waitcnt lgkmcnt(1)
	v_add_f32_e32 v135, v132, v133
	v_mov_b32_e32 v132, v97
	v_mov_b32_e32 v97, v99
	v_mov_b32_e32 v133, v98
	v_pk_mul_f32 v[96:97], v[96:97], v[112:113]
	ds_bpermute_b32 v136, v117, v135
	v_pk_fma_f32 v[96:97], v[132:133], v[108:109], v[96:97]
	s_nop 0
	v_add_f32_e32 v98, v96, v97
	v_mov_b32_e32 v96, v93
	v_mov_b32_e32 v93, v95
	v_mov_b32_e32 v97, v94
	v_pk_mul_f32 v[92:93], v[92:93], v[112:113]
	ds_bpermute_b32 v99, v114, v98
	v_pk_fma_f32 v[92:93], v[96:97], v[108:109], v[92:93]
	s_waitcnt lgkmcnt(0)
	v_add_f32_e32 v96, v98, v99
	v_add_f32_e32 v94, v92, v93
	ds_bpermute_b32 v95, v114, v94
	ds_bpermute_b32 v97, v115, v96
	v_add_f32_e32 v93, v131, v134
	v_add_f32_e32 v92, v135, v136
	s_waitcnt lgkmcnt(1)
	v_add_f32_e32 v98, v94, v95
	v_mov_b32_e32 v94, v89
	v_mov_b32_e32 v89, v91
	v_mov_b32_e32 v95, v90
	v_pk_mul_f32 v[88:89], v[88:89], v[112:113]
	s_waitcnt lgkmcnt(0)
	v_add_f32_e32 v90, v96, v97
	v_pk_fma_f32 v[88:89], v[94:95], v[108:109], v[88:89]
	ds_bpermute_b32 v91, v116, v90
	v_add_f32_e32 v88, v88, v89
	ds_bpermute_b32 v89, v114, v88
	ds_bpermute_b32 v99, v115, v98
	s_waitcnt lgkmcnt(2)
	v_add_f32_e32 v90, v90, v91
	ds_bpermute_b32 v91, v117, v90
	s_waitcnt lgkmcnt(2)
	v_add_f32_e32 v88, v88, v89
	ds_bpermute_b32 v89, v115, v88
	s_waitcnt lgkmcnt(2)
	v_add_f32_e32 v94, v98, v99
	ds_bpermute_b32 v95, v116, v94
	s_waitcnt lgkmcnt(1)
	v_add_f32_e32 v96, v88, v89
	v_mov_b32_e32 v88, v85
	v_mov_b32_e32 v85, v87
	v_mov_b32_e32 v89, v86
	v_pk_mul_f32 v[84:85], v[84:85], v[112:113]
	ds_bpermute_b32 v97, v116, v96
	v_pk_fma_f32 v[84:85], v[88:89], v[108:109], v[84:85]
	s_waitcnt lgkmcnt(1)
	v_add_f32_e32 v94, v94, v95
	v_add_f32_e32 v86, v84, v85
	ds_bpermute_b32 v87, v114, v86
	v_add_f32_e32 v85, v90, v91
	s_waitcnt lgkmcnt(1)
	v_add_f32_e32 v88, v96, v97
	ds_bpermute_b32 v95, v117, v94
	ds_bpermute_b32 v89, v117, v88
	s_waitcnt lgkmcnt(2)
	v_add_f32_e32 v90, v86, v87
	v_mov_b32_e32 v86, v81
	v_mov_b32_e32 v81, v83
	ds_bpermute_b32 v91, v115, v90
	v_mov_b32_e32 v87, v82
	v_pk_mul_f32 v[80:81], v[80:81], v[112:113]
	s_waitcnt lgkmcnt(2)
	v_add_f32_e32 v84, v94, v95
	v_pk_fma_f32 v[80:81], v[86:87], v[108:109], v[80:81]
	s_nop 0
	v_add_f32_e32 v82, v80, v81
	v_mov_b32_e32 v80, v77
	v_mov_b32_e32 v77, v79
	v_mov_b32_e32 v81, v78
	v_pk_mul_f32 v[76:77], v[76:77], v[112:113]
	s_waitcnt lgkmcnt(0)
	v_add_f32_e32 v78, v90, v91
	v_pk_fma_f32 v[76:77], v[80:81], v[108:109], v[76:77]
	ds_bpermute_b32 v79, v116, v78
	v_add_f32_e32 v76, v76, v77
	ds_bpermute_b32 v77, v114, v76
	ds_bpermute_b32 v83, v114, v82
	s_waitcnt lgkmcnt(2)
	v_add_f32_e32 v78, v78, v79
	ds_bpermute_b32 v79, v117, v78
	s_waitcnt lgkmcnt(2)
	v_add_f32_e32 v76, v76, v77
	ds_bpermute_b32 v77, v115, v76
	s_waitcnt lgkmcnt(2)
	v_add_f32_e32 v80, v82, v83
	ds_bpermute_b32 v81, v115, v80
	s_waitcnt lgkmcnt(1)
	v_add_f32_e32 v82, v76, v77
	v_add_f32_e32 v76, v78, v79
	v_mov_b32_e32 v78, v73
	v_mov_b32_e32 v73, v75
	v_mov_b32_e32 v79, v74
	v_pk_mul_f32 v[72:73], v[72:73], v[112:113]
	ds_bpermute_b32 v83, v116, v82
	v_pk_fma_f32 v[72:73], v[78:79], v[108:109], v[72:73]
	s_waitcnt lgkmcnt(1)
	v_add_f32_e32 v80, v80, v81
	v_add_f32_e32 v74, v72, v73
	v_mov_b32_e32 v72, v69
	v_mov_b32_e32 v69, v71
	v_mov_b32_e32 v73, v70
	v_pk_mul_f32 v[68:69], v[68:69], v[112:113]
	ds_bpermute_b32 v75, v114, v74
	v_pk_fma_f32 v[68:69], v[72:73], v[108:109], v[68:69]
	s_waitcnt lgkmcnt(1)
	v_add_f32_e32 v82, v82, v83
	v_add_f32_e32 v70, v68, v69
	ds_bpermute_b32 v71, v114, v70
	s_waitcnt lgkmcnt(1)
	v_add_f32_e32 v72, v74, v75
	ds_bpermute_b32 v73, v115, v72
	ds_bpermute_b32 v83, v117, v82
	ds_bpermute_b32 v81, v116, v80
	s_waitcnt lgkmcnt(3)
	v_add_f32_e32 v74, v70, v71
	v_mov_b32_e32 v70, v65
	v_mov_b32_e32 v65, v67
	v_mov_b32_e32 v71, v66
	v_pk_mul_f32 v[64:65], v[64:65], v[112:113]
	s_waitcnt lgkmcnt(2)
	v_add_f32_e32 v66, v72, v73
	v_pk_fma_f32 v[64:65], v[70:71], v[108:109], v[64:65]
	ds_bpermute_b32 v67, v116, v66
	v_add_f32_e32 v64, v64, v65
	ds_bpermute_b32 v65, v114, v64
	ds_bpermute_b32 v75, v115, v74
	s_waitcnt lgkmcnt(4)
	v_add_f32_e32 v68, v82, v83
	s_waitcnt lgkmcnt(2)
	v_add_f32_e32 v66, v66, v67
	ds_bpermute_b32 v67, v117, v66
	s_waitcnt lgkmcnt(2)
	v_add_f32_e32 v64, v64, v65
	ds_bpermute_b32 v65, v115, v64
	s_waitcnt lgkmcnt(2)
	v_add_f32_e32 v70, v74, v75
	ds_bpermute_b32 v71, v116, v70
	s_waitcnt lgkmcnt(2)
	v_add_f32_e32 v66, v66, v67
	v_add_f32_e32 v80, v80, v81
	s_waitcnt lgkmcnt(1)
	v_add_f32_e32 v72, v64, v65
	v_mov_b32_e32 v64, v61
	v_mov_b32_e32 v61, v63
	v_mov_b32_e32 v65, v62
	v_pk_mul_f32 v[60:61], v[60:61], v[112:113]
	ds_bpermute_b32 v81, v117, v80
	v_pk_fma_f32 v[60:61], v[64:65], v[108:109], v[60:61]
	ds_bpermute_b32 v73, v116, v72
	v_add_f32_e32 v60, v60, v61
	ds_bpermute_b32 v61, v114, v60
	s_waitcnt lgkmcnt(3)
	v_add_f32_e32 v70, v70, v71
	ds_bpermute_b32 v71, v117, v70
	v_add_f32_e32 v77, v88, v89
	s_waitcnt lgkmcnt(3)
	v_add_f32_e32 v69, v80, v81
	s_waitcnt lgkmcnt(1)
	v_add_f32_e32 v65, v60, v61
	v_mov_b32_e32 v60, v57
	v_mov_b32_e32 v57, v59
	v_mov_b32_e32 v61, v58
	v_pk_mul_f32 v[56:57], v[56:57], v[112:113]
	ds_bpermute_b32 v67, v115, v65
	v_pk_fma_f32 v[56:57], v[60:61], v[108:109], v[56:57]
	v_add_f32_e32 v62, v72, v73
	v_add_f32_e32 v58, v56, v57
	v_mov_b32_e32 v56, v53
	v_mov_b32_e32 v53, v55
	v_mov_b32_e32 v57, v54
	v_pk_mul_f32 v[52:53], v[52:53], v[112:113]
	ds_bpermute_b32 v59, v114, v58
	v_pk_fma_f32 v[52:53], v[56:57], v[108:109], v[52:53]
	s_waitcnt lgkmcnt(1)
	v_add_f32_e32 v54, v65, v67
	v_add_f32_e32 v52, v52, v53
	ds_bpermute_b32 v53, v114, v52
	s_waitcnt lgkmcnt(1)
	v_add_f32_e32 v56, v58, v59
	ds_bpermute_b32 v55, v116, v54
	ds_bpermute_b32 v57, v115, v56
	ds_bpermute_b32 v63, v117, v62
	s_waitcnt lgkmcnt(3)
	v_add_f32_e32 v52, v52, v53
	ds_bpermute_b32 v53, v115, v52
	s_waitcnt lgkmcnt(3)
	v_add_f32_e32 v54, v54, v55
	s_waitcnt lgkmcnt(2)
	v_add_f32_e32 v56, v56, v57
	ds_bpermute_b32 v55, v117, v54
	ds_bpermute_b32 v57, v116, v56
	s_waitcnt lgkmcnt(2)
	v_add_f32_e32 v52, v52, v53
	ds_bpermute_b32 v53, v116, v52
	v_add_f32_e32 v64, v70, v71
	s_waitcnt lgkmcnt(2)
	v_add_f32_e32 v58, v54, v55
	s_waitcnt lgkmcnt(1)
	v_add_f32_e32 v54, v56, v57
	ds_bpermute_b32 v55, v117, v54
	s_waitcnt lgkmcnt(1)
	v_add_f32_e32 v56, v52, v53
	v_mov_b32_e32 v52, v49
	v_mov_b32_e32 v49, v51
	v_mov_b32_e32 v53, v50
	v_pk_mul_f32 v[48:49], v[48:49], v[112:113]
	s_waitcnt lgkmcnt(0)
	v_add_f32_e32 v61, v54, v55
	v_pk_fma_f32 v[48:49], v[52:53], v[108:109], v[48:49]
	ds_bpermute_b32 v57, v117, v56
	v_add_f32_e32 v50, v48, v49
	v_mov_b32_e32 v48, v45
	v_mov_b32_e32 v45, v47
	v_mov_b32_e32 v49, v46
	v_pk_mul_f32 v[44:45], v[44:45], v[112:113]
	ds_bpermute_b32 v51, v114, v50
	v_pk_fma_f32 v[44:45], v[48:49], v[108:109], v[44:45]
	s_waitcnt lgkmcnt(1)
	v_add_f32_e32 v57, v56, v57
	v_add_f32_e32 v44, v44, v45
	ds_bpermute_b32 v45, v114, v44
	s_waitcnt lgkmcnt(1)
	v_add_f32_e32 v46, v50, v51
	ds_bpermute_b32 v47, v115, v46
	v_add_f32_e32 v62, v62, v63
	s_waitcnt lgkmcnt(1)
	v_add_f32_e32 v48, v44, v45
	v_mov_b32_e32 v44, v41
	v_mov_b32_e32 v41, v43
	v_mov_b32_e32 v45, v42
	v_pk_mul_f32 v[40:41], v[40:41], v[112:113]
	s_waitcnt lgkmcnt(0)
	v_add_f32_e32 v42, v46, v47
	v_pk_fma_f32 v[40:41], v[44:45], v[108:109], v[40:41]
	ds_bpermute_b32 v49, v115, v48
	v_add_f32_e32 v40, v40, v41
	ds_bpermute_b32 v41, v114, v40
	ds_bpermute_b32 v43, v116, v42
	s_waitcnt lgkmcnt(2)
	v_add_f32_e32 v44, v48, v49
	ds_bpermute_b32 v45, v116, v44
	s_waitcnt lgkmcnt(2)
	v_add_f32_e32 v40, v40, v41
	ds_bpermute_b32 v41, v115, v40
	v_lshl_add_u64 v[48:49], v[102:103], 0, v[110:111]
	s_waitcnt lgkmcnt(2)
	v_add_f32_e32 v42, v42, v43
	s_waitcnt lgkmcnt(1)
	v_add_f32_e32 v44, v44, v45
	ds_bpermute_b32 v43, v117, v42
	s_waitcnt lgkmcnt(1)
	v_add_f32_e32 v46, v40, v41
	v_mov_b32_e32 v40, v37
	v_mov_b32_e32 v37, v39
	v_mov_b32_e32 v41, v38
	v_pk_mul_f32 v[36:37], v[36:37], v[112:113]
	ds_bpermute_b32 v45, v117, v44
	v_pk_fma_f32 v[36:37], v[40:41], v[108:109], v[36:37]
	ds_bpermute_b32 v47, v116, v46
	v_add_f32_e32 v36, v36, v37
	ds_bpermute_b32 v37, v114, v36
	s_waitcnt lgkmcnt(3)
	v_add_f32_e32 v60, v42, v43
	s_waitcnt lgkmcnt(2)
	v_add_f32_e32 v56, v44, v45
	s_waitcnt lgkmcnt(1)
	v_add_f32_e32 v38, v46, v47
	global_load_dwordx4 v[78:81], v[48:49], off
	global_load_dwordx4 v[86:89], v[48:49], off offset:2048
	s_waitcnt lgkmcnt(0)
	v_add_f32_e32 v40, v36, v37
	v_mov_b32_e32 v36, v33
	v_mov_b32_e32 v33, v35
	v_mov_b32_e32 v37, v34
	v_pk_mul_f32 v[32:33], v[32:33], v[112:113]
	ds_bpermute_b32 v41, v115, v40
	v_pk_fma_f32 v[32:33], v[36:37], v[108:109], v[32:33]
	ds_bpermute_b32 v39, v117, v38
	v_add_f32_e32 v34, v32, v33
	v_mov_b32_e32 v32, v29
	v_mov_b32_e32 v29, v31
	v_mov_b32_e32 v33, v30
	v_pk_mul_f32 v[28:29], v[28:29], v[112:113]
	ds_bpermute_b32 v35, v114, v34
	v_pk_fma_f32 v[28:29], v[32:33], v[108:109], v[28:29]
	s_waitcnt lgkmcnt(2)
	v_add_f32_e32 v30, v40, v41
	v_add_f32_e32 v28, v28, v29
	ds_bpermute_b32 v29, v114, v28
	s_waitcnt lgkmcnt(1)
	v_add_f32_e32 v32, v34, v35
	ds_bpermute_b32 v33, v115, v32
	ds_bpermute_b32 v31, v116, v30
	v_add_f32_e32 v63, v38, v39
	s_waitcnt lgkmcnt(2)
	v_add_f32_e32 v28, v28, v29
	ds_bpermute_b32 v29, v115, v28
	s_waitcnt lgkmcnt(2)
	v_add_f32_e32 v32, v32, v33
	ds_bpermute_b32 v33, v116, v32
	s_waitcnt lgkmcnt(2)
	v_add_f32_e32 v30, v30, v31
	ds_bpermute_b32 v31, v117, v30
	s_waitcnt lgkmcnt(2)
	v_add_f32_e32 v34, v28, v29
	v_mov_b32_e32 v28, v25
	v_mov_b32_e32 v25, v27
	v_mov_b32_e32 v29, v26
	v_pk_mul_f32 v[24:25], v[24:25], v[112:113]
	s_waitcnt lgkmcnt(1)
	v_add_f32_e32 v26, v32, v33
	v_pk_fma_f32 v[24:25], v[28:29], v[108:109], v[24:25]
	ds_bpermute_b32 v27, v117, v26
	v_add_f32_e32 v24, v24, v25
	ds_bpermute_b32 v25, v114, v24
	ds_bpermute_b32 v35, v116, v34
	s_waitcnt lgkmcnt(3)
	v_add_f32_e32 v59, v30, v31
	s_waitcnt lgkmcnt(2)
	v_add_f32_e32 v54, v26, v27
	s_waitcnt lgkmcnt(1)
	v_add_f32_e32 v24, v24, v25
	ds_bpermute_b32 v25, v115, v24
	s_waitcnt lgkmcnt(1)
	v_add_f32_e32 v28, v34, v35
	ds_bpermute_b32 v29, v117, v28
	s_waitcnt lgkmcnt(1)
	v_add_f32_e32 v26, v24, v25
	v_mov_b32_e32 v24, v21
	v_mov_b32_e32 v21, v23
	v_mov_b32_e32 v25, v22
	v_pk_mul_f32 v[20:21], v[20:21], v[112:113]
	ds_bpermute_b32 v27, v116, v26
	v_pk_fma_f32 v[20:21], v[24:25], v[108:109], v[20:21]
	s_waitcnt lgkmcnt(1)
	v_add_f32_e32 v52, v28, v29
	v_add_f32_e32 v22, v20, v21
	v_mov_b32_e32 v20, v17
	v_mov_b32_e32 v17, v19
	v_mov_b32_e32 v21, v18
	v_pk_mul_f32 v[16:17], v[16:17], v[112:113]
	ds_bpermute_b32 v23, v114, v22
	v_pk_fma_f32 v[16:17], v[20:21], v[108:109], v[16:17]
	s_waitcnt lgkmcnt(1)
	v_add_f32_e32 v53, v26, v27
	v_add_f32_e32 v16, v16, v17
	ds_bpermute_b32 v17, v114, v16
	s_waitcnt lgkmcnt(1)
	v_add_f32_e32 v18, v22, v23
	ds_bpermute_b32 v19, v115, v18
	ds_bpermute_b32 v55, v117, v53
	s_waitcnt lgkmcnt(2)
	v_add_f32_e32 v20, v16, v17
	v_mov_b32_e32 v16, v13
	v_mov_b32_e32 v13, v15
	v_mov_b32_e32 v17, v14
	v_pk_mul_f32 v[12:13], v[12:13], v[112:113]
	ds_bpermute_b32 v21, v115, v20
	v_pk_fma_f32 v[12:13], v[16:17], v[108:109], v[12:13]
	s_waitcnt lgkmcnt(2)
	v_add_f32_e32 v14, v18, v19
	v_add_f32_e32 v12, v12, v13
	ds_bpermute_b32 v13, v114, v12
	ds_bpermute_b32 v15, v116, v14
	s_waitcnt lgkmcnt(2)
	v_add_f32_e32 v16, v20, v21
	ds_bpermute_b32 v17, v116, v16
	v_add_f32_e32 v73, v53, v55
	s_waitcnt lgkmcnt(2)
	v_add_f32_e32 v12, v12, v13
	ds_bpermute_b32 v13, v115, v12
	s_waitcnt lgkmcnt(2)
	v_add_f32_e32 v65, v14, v15
	s_waitcnt lgkmcnt(1)
	v_add_f32_e32 v74, v16, v17
	ds_bpermute_b32 v75, v117, v74
	ds_bpermute_b32 v67, v117, v65
	s_waitcnt lgkmcnt(2)
	v_add_f32_e32 v82, v12, v13
	v_add_co_u32_e32 v12, vcc, s17, v48
	ds_bpermute_b32 v83, v116, v82
	s_nop 0
	v_addc_co_u32_e32 v13, vcc, 0, v49, vcc
	v_add_co_u32_e32 v14, vcc, s91, v48
	s_waitcnt lgkmcnt(0)
	v_add_f32_e32 v53, v82, v83
	v_addc_co_u32_e32 v15, vcc, 0, v49, vcc
	v_add_co_u32_e32 v16, vcc, s50, v48
	global_load_dwordx4 v[94:97], v[14:15], off offset:-4096
	global_load_dwordx4 v[132:135], v[14:15], off
	v_addc_co_u32_e32 v17, vcc, 0, v49, vcc
	v_add_co_u32_e32 v18, vcc, s90, v48
	ds_bpermute_b32 v55, v117, v53
	s_nop 0
	v_addc_co_u32_e32 v19, vcc, 0, v49, vcc
	global_load_dwordx4 v[136:139], v[14:15], off offset:2048
	global_load_dwordx4 v[140:143], v[18:19], off offset:-4096
	global_load_dwordx4 v[144:147], v[12:13], off offset:2048
	global_load_dwordx4 v[44:47], v[16:17], off offset:2048
	global_load_dwordx4 v[40:43], v[18:19], off
	global_load_dwordx4 v[32:35], v[18:19], off offset:2048
	v_add_co_u32_e32 v12, vcc, s96, v48
	v_add_f32_e32 v72, v65, v67
	s_nop 0
	v_addc_co_u32_e32 v13, vcc, 0, v49, vcc
	v_add_co_u32_e32 v14, vcc, s21, v48
	s_nop 1
	v_addc_co_u32_e32 v15, vcc, 0, v49, vcc
	v_add_co_u32_e32 v70, vcc, s51, v48
	global_load_dwordx4 v[36:39], v[14:15], off offset:-4096
	global_load_dwordx4 v[24:27], v[14:15], off
	v_addc_co_u32_e32 v71, vcc, 0, v49, vcc
	v_add_co_u32_e32 v50, vcc, s92, v48
	s_nop 1
	v_addc_co_u32_e32 v51, vcc, 0, v49, vcc
	global_load_dwordx4 v[20:23], v[14:15], off offset:2048
	global_load_dwordx4 v[16:19], v[50:51], off offset:-4096
	global_load_dwordx4 v[28:31], v[12:13], off offset:2048
	s_nop 0
	global_load_dwordx4 v[12:15], v[70:71], off offset:2048
	v_add_f32_e32 v70, v74, v75
	v_mov_b32_e32 v74, v9
	v_mov_b32_e32 v9, v11
	v_mov_b32_e32 v75, v10
	v_pk_mul_f32 v[8:9], v[8:9], v[112:113]
	s_waitcnt lgkmcnt(0)
	v_add_f32_e32 v71, v53, v55
	v_pk_fma_f32 v[8:9], v[74:75], v[108:109], v[8:9]
	s_nop 0
	v_add_f32_e32 v10, v8, v9
	s_waitcnt vmcnt(16)
	v_mov_b32_e32 v8, v5
	v_mov_b32_e32 v9, v6
	v_mov_b32_e32 v5, v7
	v_mul_f32_e32 v6, v108, v123
	v_mul_f32_e32 v7, v113, v124
	v_pk_mul_f32 v[4:5], v[4:5], v[112:113]
	v_fmac_f32_e32 v6, v112, v121
	v_fmac_f32_e32 v7, v109, v122
	v_pk_fma_f32 v[4:5], v[8:9], v[108:109], v[4:5]
	v_add_f32_e32 v6, v6, v7
	v_add_f32_e32 v4, v4, v5
	ds_bpermute_b32 v7, v114, v6
	ds_bpermute_b32 v5, v114, v4
	ds_bpermute_b32 v11, v114, v10
	s_waitcnt lgkmcnt(2)
	v_add_f32_e32 v6, v6, v7
	s_waitcnt lgkmcnt(1)
	v_add_f32_e32 v4, v4, v5
	ds_bpermute_b32 v7, v115, v6
	ds_bpermute_b32 v5, v115, v4
	s_waitcnt lgkmcnt(2)
	v_add_f32_e32 v8, v10, v11
	ds_bpermute_b32 v9, v115, v8
	s_waitcnt lgkmcnt(2)
	v_add_f32_e32 v6, v6, v7
	s_waitcnt lgkmcnt(1)
	v_add_f32_e32 v4, v4, v5
	ds_bpermute_b32 v7, v116, v6
	ds_bpermute_b32 v5, v116, v4
	s_waitcnt lgkmcnt(2)
	v_add_f32_e32 v8, v8, v9
	ds_bpermute_b32 v9, v116, v8
	s_waitcnt lgkmcnt(2)
	v_add_f32_e32 v6, v6, v7
	s_waitcnt lgkmcnt(1)
	v_add_f32_e32 v4, v4, v5
	ds_bpermute_b32 v7, v117, v6
	ds_bpermute_b32 v5, v117, v4
	s_waitcnt lgkmcnt(2)
	v_add_f32_e32 v8, v8, v9
	ds_bpermute_b32 v9, v117, v8
	s_waitcnt lgkmcnt(2)
	v_add_f32_e32 v53, v6, v7
	s_waitcnt lgkmcnt(1)
	v_add_f32_e32 v65, v4, v5
	v_cndmask_b32_e64 v4, v130, v237, s[38:39]
	v_max_f32_e32 v5, v53, v120
	v_max3_f32 v5, v5, v4, v126
	v_max3_f32 v5, v5, v128, v125
	v_max3_f32 v5, v5, v129, v127
	v_max3_f32 v5, v5, v93, v92
	v_max3_f32 v5, v5, v85, v84
	v_max3_f32 v5, v5, v77, v76
	v_max3_f32 v5, v5, v69, v68
	v_max3_f32 v5, v5, v66, v64
	v_max3_f32 v5, v5, v62, v58
	v_max3_f32 v5, v5, v61, v57
	v_max3_f32 v5, v5, v60, v56
	v_max3_f32 v5, v5, v63, v59
	v_max3_f32 v5, v5, v54, v52
	v_max3_f32 v5, v5, v73, v72
	s_waitcnt lgkmcnt(0)
	v_add_f32_e32 v67, v8, v9
	v_max3_f32 v5, v5, v70, v71
	v_max3_f32 v5, v5, v67, v65
	ds_bpermute_b32 v6, v118, v5
	s_waitcnt lgkmcnt(0)
	v_max_f32_e32 v6, v6, v6
	v_max_f32_e32 v5, v5, v6
	ds_bpermute_b32 v6, v119, v5
	s_waitcnt lgkmcnt(0)
	v_max_f32_e32 v6, v6, v6
	v_max_f32_e32 v55, v5, v6
	v_sub_f32_e32 v4, v4, v55
	v_exp_f32_e32 v4, v4
	v_sub_f32_e32 v8, v126, v55
	v_exp_f32_e32 v8, v8
	v_add_f32_e32 v9, 0, v4
	s_waitcnt vmcnt(15)
	v_pk_fma_f32 v[6:7], v[78:79], v[4:5], 0 op_sel_hi:[1,0,0]
	v_pk_fma_f32 v[4:5], v[80:81], v[4:5], 0 op_sel_hi:[1,0,0]
	v_add_f32_e32 v9, v8, v9
	s_waitcnt vmcnt(14)
	v_pk_fma_f32 v[4:5], v[88:89], v[8:9], v[4:5] op_sel_hi:[1,0,1]
	v_pk_fma_f32 v[6:7], v[86:87], v[8:9], v[6:7] op_sel_hi:[1,0,1]
	v_sub_f32_e32 v8, v128, v55
	v_exp_f32_e32 v8, v8
	s_nop 0
	v_add_f32_e32 v9, v8, v9
	s_waitcnt vmcnt(13)
	v_pk_fma_f32 v[6:7], v[94:95], v[8:9], v[6:7] op_sel_hi:[1,0,1]
	v_pk_fma_f32 v[4:5], v[96:97], v[8:9], v[4:5] op_sel_hi:[1,0,1]
	v_sub_f32_e32 v8, v125, v55
	v_exp_f32_e32 v8, v8
	s_nop 0
	v_add_f32_e32 v9, v8, v9
	s_waitcnt vmcnt(9)
	v_pk_fma_f32 v[4:5], v[146:147], v[8:9], v[4:5] op_sel_hi:[1,0,1]
	v_pk_fma_f32 v[6:7], v[144:145], v[8:9], v[6:7] op_sel_hi:[1,0,1]
	v_sub_f32_e32 v8, v129, v55
	v_exp_f32_e32 v8, v8
	s_nop 0
	v_add_f32_e32 v9, v8, v9
	v_pk_fma_f32 v[6:7], v[132:133], v[8:9], v[6:7] op_sel_hi:[1,0,1]
	v_pk_fma_f32 v[4:5], v[134:135], v[8:9], v[4:5] op_sel_hi:[1,0,1]
	v_sub_f32_e32 v8, v127, v55
	v_exp_f32_e32 v8, v8
	s_nop 0
	v_add_f32_e32 v9, v8, v9
	v_pk_fma_f32 v[4:5], v[138:139], v[8:9], v[4:5] op_sel_hi:[1,0,1]
	v_pk_fma_f32 v[6:7], v[136:137], v[8:9], v[6:7] op_sel_hi:[1,0,1]
	v_sub_f32_e32 v8, v93, v55
	v_exp_f32_e32 v8, v8
	s_nop 0
	v_add_f32_e32 v9, v8, v9
	v_pk_fma_f32 v[6:7], v[140:141], v[8:9], v[6:7] op_sel_hi:[1,0,1]
	v_pk_fma_f32 v[4:5], v[142:143], v[8:9], v[4:5] op_sel_hi:[1,0,1]
	v_sub_f32_e32 v8, v92, v55
	v_exp_f32_e32 v8, v8
	s_nop 0
	v_add_f32_e32 v9, v8, v9
	s_waitcnt vmcnt(8)
	v_pk_fma_f32 v[4:5], v[46:47], v[8:9], v[4:5] op_sel_hi:[1,0,1]
	v_pk_fma_f32 v[6:7], v[44:45], v[8:9], v[6:7] op_sel_hi:[1,0,1]
	v_sub_f32_e32 v8, v85, v55
	v_exp_f32_e32 v8, v8
	s_nop 0
	v_add_f32_e32 v9, v8, v9
	s_waitcnt vmcnt(7)
	v_pk_fma_f32 v[6:7], v[40:41], v[8:9], v[6:7] op_sel_hi:[1,0,1]
	v_pk_fma_f32 v[4:5], v[42:43], v[8:9], v[4:5] op_sel_hi:[1,0,1]
	v_sub_f32_e32 v8, v84, v55
	v_exp_f32_e32 v8, v8
	s_nop 0
	v_add_f32_e32 v9, v8, v9
	s_waitcnt vmcnt(6)
	v_pk_fma_f32 v[4:5], v[34:35], v[8:9], v[4:5] op_sel_hi:[1,0,1]
	v_pk_fma_f32 v[6:7], v[32:33], v[8:9], v[6:7] op_sel_hi:[1,0,1]
	v_sub_f32_e32 v8, v77, v55
	v_exp_f32_e32 v8, v8
	s_nop 0
	v_add_f32_e32 v9, v8, v9
	s_waitcnt vmcnt(5)
	v_pk_fma_f32 v[6:7], v[36:37], v[8:9], v[6:7] op_sel_hi:[1,0,1]
	v_pk_fma_f32 v[4:5], v[38:39], v[8:9], v[4:5] op_sel_hi:[1,0,1]
	v_sub_f32_e32 v8, v76, v55
	v_exp_f32_e32 v8, v8
	s_nop 0
	v_add_f32_e32 v9, v8, v9
	s_waitcnt vmcnt(1)
	v_pk_fma_f32 v[4:5], v[30:31], v[8:9], v[4:5] op_sel_hi:[1,0,1]
	v_pk_fma_f32 v[6:7], v[28:29], v[8:9], v[6:7] op_sel_hi:[1,0,1]
	v_sub_f32_e32 v8, v69, v55
	v_exp_f32_e32 v8, v8
	s_nop 0
	v_add_f32_e32 v9, v8, v9
	v_pk_fma_f32 v[6:7], v[24:25], v[8:9], v[6:7] op_sel_hi:[1,0,1]
	v_pk_fma_f32 v[4:5], v[26:27], v[8:9], v[4:5] op_sel_hi:[1,0,1]
	v_sub_f32_e32 v8, v68, v55
	v_exp_f32_e32 v8, v8
	s_nop 0
	v_add_f32_e32 v9, v8, v9
	v_pk_fma_f32 v[4:5], v[22:23], v[8:9], v[4:5] op_sel_hi:[1,0,1]
	v_pk_fma_f32 v[6:7], v[20:21], v[8:9], v[6:7] op_sel_hi:[1,0,1]
	v_sub_f32_e32 v8, v66, v55
	v_exp_f32_e32 v8, v8
	s_nop 0
	v_add_f32_e32 v9, v8, v9
	v_pk_fma_f32 v[6:7], v[16:17], v[8:9], v[6:7] op_sel_hi:[1,0,1]
	v_pk_fma_f32 v[4:5], v[18:19], v[8:9], v[4:5] op_sel_hi:[1,0,1]
	v_sub_f32_e32 v8, v64, v55
	v_exp_f32_e32 v8, v8
	s_nop 0
	v_add_f32_e32 v64, v8, v9
	s_waitcnt vmcnt(0)
	v_pk_fma_f32 v[68:69], v[14:15], v[8:9], v[4:5] op_sel_hi:[1,0,1]
	v_pk_fma_f32 v[90:91], v[12:13], v[8:9], v[6:7] op_sel_hi:[1,0,1]
	v_add_co_u32_e32 v4, vcc, s56, v48
	s_nop 1
	v_addc_co_u32_e32 v5, vcc, 0, v49, vcc
	v_add_co_u32_e32 v6, vcc, s93, v48
	s_nop 1
	v_addc_co_u32_e32 v7, vcc, 0, v49, vcc
	global_load_dwordx4 v[28:31], v[50:51], off offset:2048
	global_load_dwordx4 v[32:35], v[6:7], off offset:-4096
	global_load_dwordx4 v[36:39], v[6:7], off
	global_load_dwordx4 v[40:43], v[6:7], off offset:2048
	v_add_co_u32_e32 v6, vcc, s57, v48
	s_nop 1
	v_addc_co_u32_e32 v7, vcc, 0, v49, vcc
	v_add_co_u32_e32 v8, vcc, s6, v48
	s_nop 1
	v_addc_co_u32_e32 v9, vcc, 0, v49, vcc
	global_load_dwordx4 v[44:47], v[4:5], off offset:2048
	global_load_dwordx4 v[74:77], v[6:7], off offset:2048
	global_load_dwordx4 v[78:81], v[8:9], off offset:-4096
	global_load_dwordx4 v[82:85], v[8:9], off
	v_add_co_u32_e32 v4, vcc, s58, v48
	s_nop 1
	v_addc_co_u32_e32 v5, vcc, 0, v49, vcc
	v_add_co_u32_e32 v6, vcc, s95, v48
	s_nop 1
	v_addc_co_u32_e32 v7, vcc, 0, v49, vcc
	global_load_dwordx4 v[86:89], v[8:9], off offset:2048
	global_load_dwordx4 v[24:27], v[6:7], off offset:-4096
	global_load_dwordx4 v[16:19], v[6:7], off
	global_load_dwordx4 v[12:15], v[6:7], off offset:2048
	v_add_co_u32_e32 v6, vcc, s52, v48
	s_nop 1
	v_addc_co_u32_e32 v7, vcc, 0, v49, vcc
	global_load_dwordx4 v[20:23], v[4:5], off offset:2048
	global_load_dwordx4 v[8:11], v[6:7], off
	s_nop 0
	global_load_dwordx4 v[48:51], v[50:51], off
	s_nop 0
	global_load_dwordx4 v[4:7], v[6:7], off offset:2048
	v_sub_f32_e32 v62, v62, v55
	v_exp_f32_e32 v62, v62
	v_sub_f32_e32 v58, v58, v55
	v_exp_f32_e32 v58, v58
	s_waitcnt vmcnt(1)
	v_pk_fma_f32 v[48:49], v[48:49], v[62:63], v[90:91] op_sel_hi:[1,0,1]
	v_add_f32_e32 v64, v62, v64
	v_pk_fma_f32 v[28:29], v[28:29], v[58:59], v[48:49] op_sel_hi:[1,0,1]
	v_sub_f32_e32 v48, v61, v55
	v_exp_f32_e32 v48, v48
	v_pk_fma_f32 v[50:51], v[50:51], v[62:63], v[68:69] op_sel_hi:[1,0,1]
	v_add_f32_e32 v62, v58, v64
	v_pk_fma_f32 v[30:31], v[30:31], v[58:59], v[50:51] op_sel_hi:[1,0,1]
	v_add_f32_e32 v49, v48, v62
	v_pk_fma_f32 v[28:29], v[32:33], v[48:49], v[28:29] op_sel_hi:[1,0,1]
	v_sub_f32_e32 v32, v57, v55
	v_exp_f32_e32 v32, v32
	v_pk_fma_f32 v[30:31], v[34:35], v[48:49], v[30:31] op_sel_hi:[1,0,1]
	v_add_f32_e32 v33, v32, v49
	v_pk_fma_f32 v[30:31], v[46:47], v[32:33], v[30:31] op_sel_hi:[1,0,1]
	v_pk_fma_f32 v[28:29], v[44:45], v[32:33], v[28:29] op_sel_hi:[1,0,1]
	v_sub_f32_e32 v32, v60, v55
	v_exp_f32_e32 v32, v32
	s_nop 0
	v_add_f32_e32 v33, v32, v33
	v_pk_fma_f32 v[28:29], v[36:37], v[32:33], v[28:29] op_sel_hi:[1,0,1]
	v_pk_fma_f32 v[30:31], v[38:39], v[32:33], v[30:31] op_sel_hi:[1,0,1]
	v_sub_f32_e32 v32, v56, v55
	v_exp_f32_e32 v32, v32
	s_nop 0
	v_add_f32_e32 v33, v32, v33
	v_pk_fma_f32 v[30:31], v[42:43], v[32:33], v[30:31] op_sel_hi:[1,0,1]
	v_pk_fma_f32 v[28:29], v[40:41], v[32:33], v[28:29] op_sel_hi:[1,0,1]
	v_sub_f32_e32 v32, v63, v55
	v_exp_f32_e32 v32, v32
	s_nop 0
	v_add_f32_e32 v33, v32, v33
	v_pk_fma_f32 v[28:29], v[78:79], v[32:33], v[28:29] op_sel_hi:[1,0,1]
	v_pk_fma_f32 v[30:31], v[80:81], v[32:33], v[30:31] op_sel_hi:[1,0,1]
	v_sub_f32_e32 v32, v59, v55
	v_exp_f32_e32 v32, v32
	s_nop 0
	v_add_f32_e32 v33, v32, v33
	v_pk_fma_f32 v[30:31], v[76:77], v[32:33], v[30:31] op_sel_hi:[1,0,1]
	v_pk_fma_f32 v[28:29], v[74:75], v[32:33], v[28:29] op_sel_hi:[1,0,1]
	v_sub_f32_e32 v32, v54, v55
	v_exp_f32_e32 v32, v32
	s_nop 0
	v_add_f32_e32 v33, v32, v33
	v_pk_fma_f32 v[28:29], v[82:83], v[32:33], v[28:29] op_sel_hi:[1,0,1]
	v_pk_fma_f32 v[30:31], v[84:85], v[32:33], v[30:31] op_sel_hi:[1,0,1]
	v_sub_f32_e32 v32, v52, v55
	v_exp_f32_e32 v32, v32
	s_nop 0
	v_add_f32_e32 v33, v32, v33
	v_pk_fma_f32 v[30:31], v[88:89], v[32:33], v[30:31] op_sel_hi:[1,0,1]
	v_pk_fma_f32 v[28:29], v[86:87], v[32:33], v[28:29] op_sel_hi:[1,0,1]
	v_sub_f32_e32 v32, v73, v55
	v_exp_f32_e32 v32, v32
	s_nop 0
	v_add_f32_e32 v33, v32, v33
	v_pk_fma_f32 v[24:25], v[24:25], v[32:33], v[28:29] op_sel_hi:[1,0,1]
	v_sub_f32_e32 v28, v72, v55
	v_exp_f32_e32 v28, v28
	v_pk_fma_f32 v[26:27], v[26:27], v[32:33], v[30:31] op_sel_hi:[1,0,1]
	v_add_f32_e32 v29, v28, v33
	v_pk_fma_f32 v[20:21], v[20:21], v[28:29], v[24:25] op_sel_hi:[1,0,1]
	v_sub_f32_e32 v24, v70, v55
	v_exp_f32_e32 v24, v24
	v_pk_fma_f32 v[22:23], v[22:23], v[28:29], v[26:27] op_sel_hi:[1,0,1]
	v_add_f32_e32 v25, v24, v29
	v_pk_fma_f32 v[16:17], v[16:17], v[24:25], v[20:21] op_sel_hi:[1,0,1]
	v_sub_f32_e32 v20, v71, v55
	v_exp_f32_e32 v20, v20
	v_pk_fma_f32 v[18:19], v[18:19], v[24:25], v[22:23] op_sel_hi:[1,0,1]
	v_add_f32_e32 v21, v20, v25
	v_pk_fma_f32 v[12:13], v[12:13], v[20:21], v[16:17] op_sel_hi:[1,0,1]
	v_sub_f32_e32 v16, v67, v55
	v_exp_f32_e32 v16, v16
	v_pk_fma_f32 v[14:15], v[14:15], v[20:21], v[18:19] op_sel_hi:[1,0,1]
	v_add_f32_e32 v17, v16, v21
	v_pk_fma_f32 v[8:9], v[8:9], v[16:17], v[12:13] op_sel_hi:[1,0,1]
	v_sub_f32_e32 v12, v65, v55
	v_exp_f32_e32 v12, v12
	v_pk_fma_f32 v[10:11], v[10:11], v[16:17], v[14:15] op_sel_hi:[1,0,1]
	v_add_f32_e32 v13, v12, v17
	s_waitcnt vmcnt(0)
	v_pk_fma_f32 v[10:11], v[6:7], v[12:13], v[10:11] op_sel_hi:[1,0,1]
	v_pk_fma_f32 v[4:5], v[4:5], v[12:13], v[8:9] op_sel_hi:[1,0,1]
	ds_bpermute_b32 v12, v118, v13
	ds_bpermute_b32 v6, v118, v4
	ds_bpermute_b32 v7, v118, v5
	ds_bpermute_b32 v8, v118, v10
	ds_bpermute_b32 v9, v118, v11
	s_waitcnt lgkmcnt(4)
	v_add_f32_e32 v12, v13, v12
	ds_bpermute_b32 v13, v119, v12
	s_waitcnt lgkmcnt(3)
	v_pk_add_f32 v[4:5], v[4:5], v[6:7]
	ds_bpermute_b32 v6, v119, v4
	s_waitcnt lgkmcnt(2)
	v_pk_add_f32 v[8:9], v[10:11], v[8:9]
	ds_bpermute_b32 v7, v119, v5
	ds_bpermute_b32 v10, v119, v8
	ds_bpermute_b32 v11, v119, v9
	s_and_saveexec_b64 s[30:31], s[38:39]
	s_cbranch_execz .LBB0_531
	global_load_dwordx2 v[14:15], v2, s[22:23] offset:2048
	s_waitcnt lgkmcnt(2)
	v_pk_add_f32 v[4:5], v[4:5], v[6:7]
	s_waitcnt lgkmcnt(0)
	v_pk_add_f32 v[6:7], v[8:9], v[10:11]
	v_sub_f32_e32 v8, v53, v55
	v_sub_f32_e32 v9, v120, v55
	v_exp_f32_e32 v8, v8
	v_exp_f32_e32 v9, v9
	v_add_f32_e32 v12, v12, v13
	s_lshl_b32 s21, s41, 6
	v_lshlrev_b32_e32 v18, 16, v107
	v_and_b32_e32 v19, 0xffff0000, v107
	s_mul_hi_i32 s22, s20, 0xc00
	s_mulk_i32 s20, 0xc00
	v_add_f32_e32 v10, v8, v12
	s_add_u32 s20, s34, s20
	v_pk_fma_f32 v[6:7], v[8:9], v[18:19], v[6:7] op_sel_hi:[0,1,1]
	v_add_f32_e32 v9, v9, v10
	s_addc_u32 s24, s35, s22
	v_div_scale_f32 v10, s[22:23], v9, v9, 1.0
	v_rcp_f32_e32 v11, v10
	v_lshlrev_b32_e32 v16, 16, v106
	v_and_b32_e32 v17, 0xffff0000, v106
	v_pk_fma_f32 v[4:5], v[8:9], v[16:17], v[4:5] op_sel_hi:[0,1,1]
	v_fma_f32 v12, -v10, v11, 1.0
	v_div_scale_f32 v8, vcc, 1.0, v9, 1.0
	v_fmac_f32_e32 v11, v12, v11
	v_mul_f32_e32 v12, v8, v11
	v_fma_f32 v13, -v10, v12, v8
	v_fmac_f32_e32 v12, v13, v11
	v_fma_f32 v8, -v10, v12, v8
	v_div_fmas_f32 v8, v8, v11, v12
	v_div_fixup_f32 v8, v8, v9, 1.0
	s_lshl_b32 s21, s21, 1
	v_mul_f32_e32 v4, v8, v4
	v_mul_f32_e32 v5, v8, v5
	v_mul_f32_e32 v6, v8, v6
	v_mul_f32_e32 v7, v8, v7
	s_add_u32 s20, s20, s21
	s_addc_u32 s21, s24, 0
	s_waitcnt vmcnt(0)
	v_lshlrev_b32_e32 v8, 16, v14
	v_and_b32_e32 v9, 0xffff0000, v14
	v_lshlrev_b32_e32 v10, 16, v15
	v_and_b32_e32 v11, 0xffff0000, v15
	v_mul_f32_e32 v4, v4, v8
	v_mul_f32_e32 v5, v5, v9
	v_mul_f32_e32 v6, v6, v10
	v_mul_f32_e32 v7, v7, v11
	v_cvt_pk_bf16_f32 v4, v4, v5
	v_cvt_pk_bf16_f32 v5, v6, v7
	global_store_dwordx2 v2, v[4:5], s[20:21] sc1
	s_branch .LBB0_531

.LBB0_631:
	s_ashr_i32 s1, s80, 4
	s_add_i32 s20, s1, 0x4000
	s_and_b32 s0, s80, 15
	s_ashr_i32 s21, s20, 31
	s_mul_i32 s14, s20, 0x1800
	s_mul_hi_i32 s4, s20, 0x1800
	s_add_u32 s14, s72, s14
	s_addc_u32 s4, s73, s4
	s_lshl_b32 s22, s0, 7
	s_add_u32 s22, s14, s22
	s_addc_u32 s23, s4, 0
	s_lshl_b64 s[28:29], s[20:21], 8
	s_add_u32 s4, s34, s28
	s_addc_u32 s14, s35, s29
	s_lshl_b32 s21, s80, 3
	s_and_b32 s21, s21, 64
	s_lshl_b32 s24, s21, 1
	s_add_u32 s30, s4, s24
	s_addc_u32 s31, s14, 0
	s_add_u32 s4, s78, s28
	s_addc_u32 s14, s79, s29
	s_add_u32 s28, s4, s24
	s_waitcnt vmcnt(24) lgkmcnt(2)
	v_lshl_add_u64 v[6:7], s[30:31], 0, v[104:105]
	s_addc_u32 s29, s14, 0
	v_lshl_add_u64 v[4:5], s[22:23], 0, v[104:105]
	global_load_dwordx2 v[6:7], v[6:7], off
	s_nop 0
	global_load_dwordx2 v[106:107], v2, s[28:29]
	global_load_dwordx2 v[112:113], v[4:5], off
	s_or_b32 s28, s0, s74
	s_ashr_i32 s29, s28, 31
	s_lshl_b64 s[28:29], s[28:29], 2
	s_add_u32 s28, s2, s28
	s_addc_u32 s29, s3, s29
	global_load_dword v120, v3, s[28:29]
	v_lshl_or_b32 v4, s1, 7, v197
	v_ashrrev_i32_e32 v5, 31, v4
	v_lshlrev_b64 v[110:111], 9, v[4:5]
	v_lshl_or_b32 v110, s21, 2, v110
	v_lshl_add_u64 v[4:5], v[100:101], 0, v[110:111]
	s_waitcnt vmcnt(3)
	v_lshlrev_b32_e32 v121, 16, v6
	v_and_b32_e32 v123, 0xffff0000, v6
	v_lshlrev_b32_e32 v122, 16, v7
	v_and_b32_e32 v124, 0xffff0000, v7
	v_add_co_u32_e32 v6, vcc, s17, v4
	global_load_dwordx4 v[126:129], v[4:5], off
	global_load_dwordx4 v[130:133], v[4:5], off offset:2048
	v_addc_co_u32_e32 v7, vcc, 0, v5, vcc
	v_add_co_u32_e32 v108, vcc, s91, v4
	s_movk_i32 s1, 0x6000
	s_nop 0
	v_addc_co_u32_e32 v109, vcc, 0, v5, vcc
	v_add_co_u32_e32 v8, vcc, s50, v4
	global_load_dwordx4 v[134:137], v[108:109], off
	global_load_dwordx4 v[138:141], v[108:109], off offset:2048
	v_addc_co_u32_e32 v9, vcc, 0, v5, vcc
	s_waitcnt lgkmcnt(1)
	v_add_co_u32_e32 v10, vcc, s90, v4
	s_waitcnt vmcnt(4)
	v_mul_f32_e32 v120, 0x3fb8aa3b, v120
	s_waitcnt lgkmcnt(0)
	v_addc_co_u32_e32 v11, vcc, 0, v5, vcc
	global_load_dwordx4 v[142:145], v[6:7], off offset:2048
	global_load_dwordx4 v[146:149], v[8:9], off offset:2048
	global_load_dwordx4 v[150:153], v[10:11], off offset:-4096
	global_load_dwordx4 v[96:99], v[10:11], off
	v_add_co_u32_e32 v6, vcc, s96, v4
	s_nop 1
	v_addc_co_u32_e32 v7, vcc, 0, v5, vcc
	v_add_co_u32_e32 v8, vcc, s1, v4
	s_nop 1
	v_addc_co_u32_e32 v9, vcc, 0, v5, vcc
	global_load_dwordx4 v[92:95], v[10:11], off offset:2048
	global_load_dwordx4 v[88:91], v[8:9], off offset:-4096
	global_load_dwordx4 v[80:83], v[8:9], off
	global_load_dwordx4 v[76:79], v[8:9], off offset:2048
	v_add_co_u32_e32 v8, vcc, s51, v4
	s_nop 1
	v_addc_co_u32_e32 v9, vcc, 0, v5, vcc
	v_add_co_u32_e32 v10, vcc, s92, v4
	s_nop 1
	v_addc_co_u32_e32 v11, vcc, 0, v5, vcc
	global_load_dwordx4 v[84:87], v[6:7], off offset:2048
	global_load_dwordx4 v[68:71], v[8:9], off offset:2048
	global_load_dwordx4 v[72:75], v[10:11], off offset:-4096
	global_load_dwordx4 v[64:67], v[10:11], off
	v_add_co_u32_e32 v6, vcc, s56, v4
	s_nop 1
	v_addc_co_u32_e32 v7, vcc, 0, v5, vcc
	v_add_co_u32_e32 v8, vcc, s93, v4
	s_nop 1
	v_addc_co_u32_e32 v9, vcc, 0, v5, vcc
	global_load_dwordx4 v[60:63], v[10:11], off offset:2048
	global_load_dwordx4 v[56:59], v[8:9], off offset:-4096
	global_load_dwordx4 v[48:51], v[8:9], off
	global_load_dwordx4 v[44:47], v[8:9], off offset:2048
	v_add_co_u32_e32 v8, vcc, s57, v4
	s_nop 1
	v_addc_co_u32_e32 v9, vcc, 0, v5, vcc
	v_add_co_u32_e32 v10, vcc, s6, v4
	s_nop 1
	v_addc_co_u32_e32 v11, vcc, 0, v5, vcc
	global_load_dwordx4 v[52:55], v[6:7], off offset:2048
	global_load_dwordx4 v[36:39], v[8:9], off offset:2048
	global_load_dwordx4 v[40:43], v[10:11], off offset:-4096
	global_load_dwordx4 v[32:35], v[10:11], off
	v_add_co_u32_e32 v6, vcc, s58, v4
	s_nop 1
	v_addc_co_u32_e32 v7, vcc, 0, v5, vcc
	v_add_co_u32_e32 v8, vcc, s95, v4
	s_nop 1
	v_addc_co_u32_e32 v9, vcc, 0, v5, vcc
	v_add_co_u32_e32 v4, vcc, s52, v4
	global_load_dwordx4 v[28:31], v[10:11], off offset:2048
	global_load_dwordx4 v[24:27], v[8:9], off offset:-4096
	global_load_dwordx4 v[16:19], v[8:9], off
	global_load_dwordx4 v[12:15], v[8:9], off offset:2048
	v_addc_co_u32_e32 v5, vcc, 0, v5, vcc
	global_load_dwordx4 v[20:23], v[6:7], off offset:2048
	global_load_dwordx4 v[8:11], v[4:5], off
	global_load_dwordx4 v[154:157], v[108:109], off offset:-4096
	s_nop 0
	global_load_dwordx4 v[4:7], v[4:5], off offset:2048
	v_and_b32_e32 v108, 0xffff0000, v112
	v_lshlrev_b32_e32 v109, 16, v113
	v_lshlrev_b32_e32 v112, 16, v112
	v_and_b32_e32 v113, 0xffff0000, v113
	s_waitcnt vmcnt(31)
	v_mov_b32_e32 v158, v127
	v_mov_b32_e32 v127, v129
	v_mov_b32_e32 v159, v128
	v_pk_mul_f32 v[126:127], v[126:127], v[112:113]
	s_movk_i32 s33, 0x6000
	v_pk_fma_f32 v[126:127], v[158:159], v[108:109], v[126:127]
	s_nop 0
	v_add_f32_e32 v125, v126, v127
	s_waitcnt vmcnt(30)
	v_mov_b32_e32 v126, v131
	v_mov_b32_e32 v131, v133
	v_mov_b32_e32 v127, v132
	v_pk_mul_f32 v[128:129], v[130:131], v[112:113]
	ds_bpermute_b32 v158, v114, v125
	v_pk_fma_f32 v[126:127], v[126:127], v[108:109], v[128:129]
	s_waitcnt lgkmcnt(0)
	v_add_f32_e32 v125, v125, v158
	v_add_f32_e32 v126, v126, v127
	ds_bpermute_b32 v127, v114, v126
	ds_bpermute_b32 v128, v115, v125
	s_waitcnt lgkmcnt(1)
	v_add_f32_e32 v126, v126, v127
	ds_bpermute_b32 v127, v115, v126
	s_waitcnt lgkmcnt(1)
	v_add_f32_e32 v125, v125, v128
	ds_bpermute_b32 v128, v116, v125
	s_waitcnt lgkmcnt(1)
	v_add_f32_e32 v126, v126, v127
	ds_bpermute_b32 v127, v116, v126
	s_waitcnt lgkmcnt(1)
	v_add_f32_e32 v125, v125, v128
	ds_bpermute_b32 v130, v117, v125
	s_waitcnt lgkmcnt(1)
	v_add_f32_e32 v131, v126, v127
	s_waitcnt vmcnt(1)
	v_mov_b32_e32 v126, v155
	v_mov_b32_e32 v155, v157
	v_mov_b32_e32 v127, v156
	v_pk_mul_f32 v[128:129], v[154:155], v[112:113]
	ds_bpermute_b32 v132, v117, v131
	v_pk_fma_f32 v[126:127], v[126:127], v[108:109], v[128:129]
	s_waitcnt lgkmcnt(1)
	v_add_f32_e32 v130, v125, v130
	v_add_f32_e32 v133, v126, v127
	v_mov_b32_e32 v126, v143
	v_mov_b32_e32 v143, v145
	v_mov_b32_e32 v127, v144
	v_pk_mul_f32 v[128:129], v[142:143], v[112:113]
	ds_bpermute_b32 v154, v114, v133
	v_pk_fma_f32 v[126:127], v[126:127], v[108:109], v[128:129]
	v_mov_b32_e32 v129, v136
	v_add_f32_e32 v127, v126, v127
	ds_bpermute_b32 v128, v114, v127
	s_waitcnt lgkmcnt(2)
	v_add_f32_e32 v126, v131, v132
	s_waitcnt lgkmcnt(1)
	v_add_f32_e32 v125, v133, v154
	ds_bpermute_b32 v131, v115, v125
	s_waitcnt lgkmcnt(1)
	v_add_f32_e32 v127, v127, v128
	v_mov_b32_e32 v128, v135
	v_mov_b32_e32 v135, v137
	v_pk_mul_f32 v[132:133], v[134:135], v[112:113]
	ds_bpermute_b32 v142, v115, v127
	v_pk_fma_f32 v[128:129], v[128:129], v[108:109], v[132:133]
	s_waitcnt lgkmcnt(1)
	v_add_f32_e32 v125, v125, v131
	v_add_f32_e32 v128, v128, v129
	ds_bpermute_b32 v129, v114, v128
	s_waitcnt lgkmcnt(1)
	v_add_f32_e32 v127, v127, v142
	ds_bpermute_b32 v132, v116, v127
	ds_bpermute_b32 v131, v116, v125
	s_waitcnt lgkmcnt(2)
	v_add_f32_e32 v128, v128, v129
	ds_bpermute_b32 v129, v115, v128
	s_waitcnt lgkmcnt(2)
	v_add_f32_e32 v127, v127, v132
	s_waitcnt lgkmcnt(1)
	v_add_f32_e32 v125, v125, v131
	ds_bpermute_b32 v131, v117, v125
	ds_bpermute_b32 v134, v117, v127
	s_waitcnt lgkmcnt(2)
	v_add_f32_e32 v135, v128, v129
	v_mov_b32_e32 v128, v139
	v_mov_b32_e32 v139, v141
	v_mov_b32_e32 v129, v140
	v_pk_mul_f32 v[132:133], v[138:139], v[112:113]
	ds_bpermute_b32 v136, v116, v135
	v_pk_fma_f32 v[128:129], v[128:129], v[108:109], v[132:133]
	v_mov_b32_e32 v133, v152
	v_add_f32_e32 v129, v128, v129
	ds_bpermute_b32 v132, v114, v129
	s_waitcnt lgkmcnt(3)
	v_add_f32_e32 v128, v125, v131
	s_waitcnt lgkmcnt(2)
	v_add_f32_e32 v125, v127, v134
	s_waitcnt lgkmcnt(1)
	v_add_f32_e32 v127, v135, v136
	ds_bpermute_b32 v131, v117, v127
	s_waitcnt lgkmcnt(1)
	v_add_f32_e32 v129, v129, v132
	v_mov_b32_e32 v132, v151
	v_mov_b32_e32 v151, v153
	v_pk_mul_f32 v[134:135], v[150:151], v[112:113]
	ds_bpermute_b32 v136, v115, v129
	v_pk_fma_f32 v[132:133], v[132:133], v[108:109], v[134:135]
	s_waitcnt lgkmcnt(0)
	v_add_f32_e32 v129, v129, v136
	v_add_f32_e32 v137, v132, v133
	v_mov_b32_e32 v132, v147
	v_mov_b32_e32 v147, v149
	v_mov_b32_e32 v133, v148
	v_pk_mul_f32 v[134:135], v[146:147], v[112:113]
	ds_bpermute_b32 v138, v114, v137
	v_pk_fma_f32 v[132:133], v[132:133], v[108:109], v[134:135]
	ds_bpermute_b32 v134, v116, v129
	v_add_f32_e32 v132, v132, v133
	ds_bpermute_b32 v133, v114, v132
	s_waitcnt lgkmcnt(2)
	v_add_f32_e32 v135, v137, v138
	ds_bpermute_b32 v136, v115, v135
	s_waitcnt lgkmcnt(2)
	v_add_f32_e32 v134, v129, v134
	v_add_f32_e32 v129, v127, v131
	s_waitcnt lgkmcnt(1)
	v_add_f32_e32 v132, v132, v133
	ds_bpermute_b32 v133, v115, v132
	s_waitcnt lgkmcnt(1)
	v_add_f32_e32 v135, v135, v136
	ds_bpermute_b32 v136, v116, v135
	ds_bpermute_b32 v137, v117, v134
	s_waitcnt lgkmcnt(2)
	v_add_f32_e32 v132, v132, v133
	ds_bpermute_b32 v133, v116, v132
	s_waitcnt lgkmcnt(2)
	v_add_f32_e32 v131, v135, v136
	s_waitcnt lgkmcnt(1)
	v_add_f32_e32 v127, v134, v137
	ds_bpermute_b32 v134, v117, v131
	s_waitcnt lgkmcnt(1)
	v_add_f32_e32 v135, v132, v133
	v_mov_b32_e32 v132, v97
	v_mov_b32_e32 v97, v99
	v_mov_b32_e32 v133, v98
	v_pk_mul_f32 v[96:97], v[96:97], v[112:113]
	ds_bpermute_b32 v136, v117, v135
	v_pk_fma_f32 v[96:97], v[132:133], v[108:109], v[96:97]
	s_nop 0
	v_add_f32_e32 v98, v96, v97
	v_mov_b32_e32 v96, v93
	v_mov_b32_e32 v93, v95
	v_mov_b32_e32 v97, v94
	v_pk_mul_f32 v[92:93], v[92:93], v[112:113]
	ds_bpermute_b32 v99, v114, v98
	v_pk_fma_f32 v[92:93], v[96:97], v[108:109], v[92:93]
	s_waitcnt lgkmcnt(0)
	v_add_f32_e32 v96, v98, v99
	v_add_f32_e32 v94, v92, v93
	ds_bpermute_b32 v95, v114, v94
	ds_bpermute_b32 v97, v115, v96
	v_add_f32_e32 v93, v131, v134
	v_add_f32_e32 v92, v135, v136
	s_waitcnt lgkmcnt(1)
	v_add_f32_e32 v98, v94, v95
	v_mov_b32_e32 v94, v89
	v_mov_b32_e32 v89, v91
	v_mov_b32_e32 v95, v90
	v_pk_mul_f32 v[88:89], v[88:89], v[112:113]
	s_waitcnt lgkmcnt(0)
	v_add_f32_e32 v90, v96, v97
	v_pk_fma_f32 v[88:89], v[94:95], v[108:109], v[88:89]
	ds_bpermute_b32 v91, v116, v90
	v_add_f32_e32 v88, v88, v89
	ds_bpermute_b32 v89, v114, v88
	ds_bpermute_b32 v99, v115, v98
	s_waitcnt lgkmcnt(2)
	v_add_f32_e32 v90, v90, v91
	ds_bpermute_b32 v91, v117, v90
	s_waitcnt lgkmcnt(2)
	v_add_f32_e32 v88, v88, v89
	ds_bpermute_b32 v89, v115, v88
	s_waitcnt lgkmcnt(2)
	v_add_f32_e32 v94, v98, v99
	ds_bpermute_b32 v95, v116, v94
	s_waitcnt lgkmcnt(1)
	v_add_f32_e32 v96, v88, v89
	v_mov_b32_e32 v88, v85
	v_mov_b32_e32 v85, v87
	v_mov_b32_e32 v89, v86
	v_pk_mul_f32 v[84:85], v[84:85], v[112:113]
	ds_bpermute_b32 v97, v116, v96
	v_pk_fma_f32 v[84:85], v[88:89], v[108:109], v[84:85]
	s_waitcnt lgkmcnt(1)
	v_add_f32_e32 v94, v94, v95
	v_add_f32_e32 v86, v84, v85
	ds_bpermute_b32 v87, v114, v86
	v_add_f32_e32 v85, v90, v91
	s_waitcnt lgkmcnt(1)
	v_add_f32_e32 v88, v96, v97
	ds_bpermute_b32 v95, v117, v94
	ds_bpermute_b32 v89, v117, v88
	s_waitcnt lgkmcnt(2)
	v_add_f32_e32 v90, v86, v87
	v_mov_b32_e32 v86, v81
	v_mov_b32_e32 v81, v83
	ds_bpermute_b32 v91, v115, v90
	v_mov_b32_e32 v87, v82
	v_pk_mul_f32 v[80:81], v[80:81], v[112:113]
	s_waitcnt lgkmcnt(2)
	v_add_f32_e32 v84, v94, v95
	v_pk_fma_f32 v[80:81], v[86:87], v[108:109], v[80:81]
	s_nop 0
	v_add_f32_e32 v82, v80, v81
	v_mov_b32_e32 v80, v77
	v_mov_b32_e32 v77, v79
	v_mov_b32_e32 v81, v78
	v_pk_mul_f32 v[76:77], v[76:77], v[112:113]
	s_waitcnt lgkmcnt(0)
	v_add_f32_e32 v78, v90, v91
	v_pk_fma_f32 v[76:77], v[80:81], v[108:109], v[76:77]
	ds_bpermute_b32 v79, v116, v78
	v_add_f32_e32 v76, v76, v77
	ds_bpermute_b32 v77, v114, v76
	ds_bpermute_b32 v83, v114, v82
	s_waitcnt lgkmcnt(2)
	v_add_f32_e32 v78, v78, v79
	ds_bpermute_b32 v79, v117, v78
	s_waitcnt lgkmcnt(2)
	v_add_f32_e32 v76, v76, v77
	ds_bpermute_b32 v77, v115, v76
	s_waitcnt lgkmcnt(2)
	v_add_f32_e32 v80, v82, v83
	ds_bpermute_b32 v81, v115, v80
	s_waitcnt lgkmcnt(1)
	v_add_f32_e32 v82, v76, v77
	v_add_f32_e32 v76, v78, v79
	v_mov_b32_e32 v78, v73
	v_mov_b32_e32 v73, v75
	v_mov_b32_e32 v79, v74
	v_pk_mul_f32 v[72:73], v[72:73], v[112:113]
	ds_bpermute_b32 v83, v116, v82
	v_pk_fma_f32 v[72:73], v[78:79], v[108:109], v[72:73]
	s_waitcnt lgkmcnt(1)
	v_add_f32_e32 v80, v80, v81
	v_add_f32_e32 v74, v72, v73
	v_mov_b32_e32 v72, v69
	v_mov_b32_e32 v69, v71
	v_mov_b32_e32 v73, v70
	v_pk_mul_f32 v[68:69], v[68:69], v[112:113]
	ds_bpermute_b32 v75, v114, v74
	v_pk_fma_f32 v[68:69], v[72:73], v[108:109], v[68:69]
	s_waitcnt lgkmcnt(1)
	v_add_f32_e32 v82, v82, v83
	v_add_f32_e32 v70, v68, v69
	ds_bpermute_b32 v71, v114, v70
	s_waitcnt lgkmcnt(1)
	v_add_f32_e32 v72, v74, v75
	ds_bpermute_b32 v73, v115, v72
	ds_bpermute_b32 v83, v117, v82
	ds_bpermute_b32 v81, v116, v80
	s_waitcnt lgkmcnt(3)
	v_add_f32_e32 v74, v70, v71
	v_mov_b32_e32 v70, v65
	v_mov_b32_e32 v65, v67
	v_mov_b32_e32 v71, v66
	v_pk_mul_f32 v[64:65], v[64:65], v[112:113]
	s_waitcnt lgkmcnt(2)
	v_add_f32_e32 v66, v72, v73
	v_pk_fma_f32 v[64:65], v[70:71], v[108:109], v[64:65]
	ds_bpermute_b32 v67, v116, v66
	v_add_f32_e32 v64, v64, v65
	ds_bpermute_b32 v65, v114, v64
	ds_bpermute_b32 v75, v115, v74
	s_waitcnt lgkmcnt(4)
	v_add_f32_e32 v68, v82, v83
	s_waitcnt lgkmcnt(2)
	v_add_f32_e32 v66, v66, v67
	ds_bpermute_b32 v67, v117, v66
	s_waitcnt lgkmcnt(2)
	v_add_f32_e32 v64, v64, v65
	ds_bpermute_b32 v65, v115, v64
	s_waitcnt lgkmcnt(2)
	v_add_f32_e32 v70, v74, v75
	ds_bpermute_b32 v71, v116, v70
	s_waitcnt lgkmcnt(2)
	v_add_f32_e32 v66, v66, v67
	v_add_f32_e32 v80, v80, v81
	s_waitcnt lgkmcnt(1)
	v_add_f32_e32 v72, v64, v65
	v_mov_b32_e32 v64, v61
	v_mov_b32_e32 v61, v63
	v_mov_b32_e32 v65, v62
	v_pk_mul_f32 v[60:61], v[60:61], v[112:113]
	ds_bpermute_b32 v81, v117, v80
	v_pk_fma_f32 v[60:61], v[64:65], v[108:109], v[60:61]
	ds_bpermute_b32 v73, v116, v72
	v_add_f32_e32 v60, v60, v61
	ds_bpermute_b32 v61, v114, v60
	s_waitcnt lgkmcnt(3)
	v_add_f32_e32 v70, v70, v71
	ds_bpermute_b32 v71, v117, v70
	v_add_f32_e32 v77, v88, v89
	s_waitcnt lgkmcnt(3)
	v_add_f32_e32 v69, v80, v81
	s_waitcnt lgkmcnt(1)
	v_add_f32_e32 v65, v60, v61
	v_mov_b32_e32 v60, v57
	v_mov_b32_e32 v57, v59
	v_mov_b32_e32 v61, v58
	v_pk_mul_f32 v[56:57], v[56:57], v[112:113]
	ds_bpermute_b32 v67, v115, v65
	v_pk_fma_f32 v[56:57], v[60:61], v[108:109], v[56:57]
	v_add_f32_e32 v62, v72, v73
	v_add_f32_e32 v58, v56, v57
	v_mov_b32_e32 v56, v53
	v_mov_b32_e32 v53, v55
	v_mov_b32_e32 v57, v54
	v_pk_mul_f32 v[52:53], v[52:53], v[112:113]
	ds_bpermute_b32 v59, v114, v58
	v_pk_fma_f32 v[52:53], v[56:57], v[108:109], v[52:53]
	s_waitcnt lgkmcnt(1)
	v_add_f32_e32 v54, v65, v67
	v_add_f32_e32 v52, v52, v53
	ds_bpermute_b32 v53, v114, v52
	s_waitcnt lgkmcnt(1)
	v_add_f32_e32 v56, v58, v59
	ds_bpermute_b32 v55, v116, v54
	ds_bpermute_b32 v57, v115, v56
	ds_bpermute_b32 v63, v117, v62
	s_waitcnt lgkmcnt(3)
	v_add_f32_e32 v52, v52, v53
	ds_bpermute_b32 v53, v115, v52
	s_waitcnt lgkmcnt(3)
	v_add_f32_e32 v54, v54, v55
	s_waitcnt lgkmcnt(2)
	v_add_f32_e32 v56, v56, v57
	ds_bpermute_b32 v55, v117, v54
	ds_bpermute_b32 v57, v116, v56
	s_waitcnt lgkmcnt(2)
	v_add_f32_e32 v52, v52, v53
	ds_bpermute_b32 v53, v116, v52
	v_add_f32_e32 v64, v70, v71
	s_waitcnt lgkmcnt(2)
	v_add_f32_e32 v58, v54, v55
	s_waitcnt lgkmcnt(1)
	v_add_f32_e32 v54, v56, v57
	ds_bpermute_b32 v55, v117, v54
	s_waitcnt lgkmcnt(1)
	v_add_f32_e32 v56, v52, v53
	v_mov_b32_e32 v52, v49
	v_mov_b32_e32 v49, v51
	v_mov_b32_e32 v53, v50
	v_pk_mul_f32 v[48:49], v[48:49], v[112:113]
	s_waitcnt lgkmcnt(0)
	v_add_f32_e32 v61, v54, v55
	v_pk_fma_f32 v[48:49], v[52:53], v[108:109], v[48:49]
	ds_bpermute_b32 v57, v117, v56
	v_add_f32_e32 v50, v48, v49
	v_mov_b32_e32 v48, v45
	v_mov_b32_e32 v45, v47
	v_mov_b32_e32 v49, v46
	v_pk_mul_f32 v[44:45], v[44:45], v[112:113]
	ds_bpermute_b32 v51, v114, v50
	v_pk_fma_f32 v[44:45], v[48:49], v[108:109], v[44:45]
	s_waitcnt lgkmcnt(1)
	v_add_f32_e32 v57, v56, v57
	v_add_f32_e32 v44, v44, v45
	ds_bpermute_b32 v45, v114, v44
	s_waitcnt lgkmcnt(1)
	v_add_f32_e32 v46, v50, v51
	ds_bpermute_b32 v47, v115, v46
	v_add_f32_e32 v62, v62, v63
	s_waitcnt lgkmcnt(1)
	v_add_f32_e32 v48, v44, v45
	v_mov_b32_e32 v44, v41
	v_mov_b32_e32 v41, v43
	v_mov_b32_e32 v45, v42
	v_pk_mul_f32 v[40:41], v[40:41], v[112:113]
	s_waitcnt lgkmcnt(0)
	v_add_f32_e32 v42, v46, v47
	v_pk_fma_f32 v[40:41], v[44:45], v[108:109], v[40:41]
	ds_bpermute_b32 v49, v115, v48
	v_add_f32_e32 v40, v40, v41
	ds_bpermute_b32 v41, v114, v40
	ds_bpermute_b32 v43, v116, v42
	s_waitcnt lgkmcnt(2)
	v_add_f32_e32 v44, v48, v49
	ds_bpermute_b32 v45, v116, v44
	s_waitcnt lgkmcnt(2)
	v_add_f32_e32 v40, v40, v41
	ds_bpermute_b32 v41, v115, v40
	v_lshl_add_u64 v[48:49], v[102:103], 0, v[110:111]
	s_waitcnt lgkmcnt(2)
	v_add_f32_e32 v42, v42, v43
	s_waitcnt lgkmcnt(1)
	v_add_f32_e32 v44, v44, v45
	ds_bpermute_b32 v43, v117, v42
	s_waitcnt lgkmcnt(1)
	v_add_f32_e32 v46, v40, v41
	v_mov_b32_e32 v40, v37
	v_mov_b32_e32 v37, v39
	v_mov_b32_e32 v41, v38
	v_pk_mul_f32 v[36:37], v[36:37], v[112:113]
	ds_bpermute_b32 v45, v117, v44
	v_pk_fma_f32 v[36:37], v[40:41], v[108:109], v[36:37]
	ds_bpermute_b32 v47, v116, v46
	v_add_f32_e32 v36, v36, v37
	ds_bpermute_b32 v37, v114, v36
	s_waitcnt lgkmcnt(3)
	v_add_f32_e32 v60, v42, v43
	s_waitcnt lgkmcnt(2)
	v_add_f32_e32 v56, v44, v45
	s_waitcnt lgkmcnt(1)
	v_add_f32_e32 v38, v46, v47
	global_load_dwordx4 v[78:81], v[48:49], off
	global_load_dwordx4 v[86:89], v[48:49], off offset:2048
	s_waitcnt lgkmcnt(0)
	v_add_f32_e32 v40, v36, v37
	v_mov_b32_e32 v36, v33
	v_mov_b32_e32 v33, v35
	v_mov_b32_e32 v37, v34
	v_pk_mul_f32 v[32:33], v[32:33], v[112:113]
	ds_bpermute_b32 v41, v115, v40
	v_pk_fma_f32 v[32:33], v[36:37], v[108:109], v[32:33]
	ds_bpermute_b32 v39, v117, v38
	v_add_f32_e32 v34, v32, v33
	v_mov_b32_e32 v32, v29
	v_mov_b32_e32 v29, v31
	v_mov_b32_e32 v33, v30
	v_pk_mul_f32 v[28:29], v[28:29], v[112:113]
	ds_bpermute_b32 v35, v114, v34
	v_pk_fma_f32 v[28:29], v[32:33], v[108:109], v[28:29]
	s_waitcnt lgkmcnt(2)
	v_add_f32_e32 v30, v40, v41
	v_add_f32_e32 v28, v28, v29
	ds_bpermute_b32 v29, v114, v28
	s_waitcnt lgkmcnt(1)
	v_add_f32_e32 v32, v34, v35
	ds_bpermute_b32 v33, v115, v32
	ds_bpermute_b32 v31, v116, v30
	v_add_f32_e32 v63, v38, v39
	s_waitcnt lgkmcnt(2)
	v_add_f32_e32 v28, v28, v29
	ds_bpermute_b32 v29, v115, v28
	s_waitcnt lgkmcnt(2)
	v_add_f32_e32 v32, v32, v33
	ds_bpermute_b32 v33, v116, v32
	s_waitcnt lgkmcnt(2)
	v_add_f32_e32 v30, v30, v31
	ds_bpermute_b32 v31, v117, v30
	s_waitcnt lgkmcnt(2)
	v_add_f32_e32 v34, v28, v29
	v_mov_b32_e32 v28, v25
	v_mov_b32_e32 v25, v27
	v_mov_b32_e32 v29, v26
	v_pk_mul_f32 v[24:25], v[24:25], v[112:113]
	s_waitcnt lgkmcnt(1)
	v_add_f32_e32 v26, v32, v33
	v_pk_fma_f32 v[24:25], v[28:29], v[108:109], v[24:25]
	ds_bpermute_b32 v27, v117, v26
	v_add_f32_e32 v24, v24, v25
	ds_bpermute_b32 v25, v114, v24
	ds_bpermute_b32 v35, v116, v34
	s_waitcnt lgkmcnt(3)
	v_add_f32_e32 v59, v30, v31
	s_waitcnt lgkmcnt(2)
	v_add_f32_e32 v54, v26, v27
	s_waitcnt lgkmcnt(1)
	v_add_f32_e32 v24, v24, v25
	ds_bpermute_b32 v25, v115, v24
	s_waitcnt lgkmcnt(1)
	v_add_f32_e32 v28, v34, v35
	ds_bpermute_b32 v29, v117, v28
	s_waitcnt lgkmcnt(1)
	v_add_f32_e32 v26, v24, v25
	v_mov_b32_e32 v24, v21
	v_mov_b32_e32 v21, v23
	v_mov_b32_e32 v25, v22
	v_pk_mul_f32 v[20:21], v[20:21], v[112:113]
	ds_bpermute_b32 v27, v116, v26
	v_pk_fma_f32 v[20:21], v[24:25], v[108:109], v[20:21]
	s_waitcnt lgkmcnt(1)
	v_add_f32_e32 v52, v28, v29
	v_add_f32_e32 v22, v20, v21
	v_mov_b32_e32 v20, v17
	v_mov_b32_e32 v17, v19
	v_mov_b32_e32 v21, v18
	v_pk_mul_f32 v[16:17], v[16:17], v[112:113]
	ds_bpermute_b32 v23, v114, v22
	v_pk_fma_f32 v[16:17], v[20:21], v[108:109], v[16:17]
	s_waitcnt lgkmcnt(1)
	v_add_f32_e32 v53, v26, v27
	v_add_f32_e32 v16, v16, v17
	ds_bpermute_b32 v17, v114, v16
	s_waitcnt lgkmcnt(1)
	v_add_f32_e32 v18, v22, v23
	ds_bpermute_b32 v19, v115, v18
	ds_bpermute_b32 v55, v117, v53
	s_waitcnt lgkmcnt(2)
	v_add_f32_e32 v20, v16, v17
	v_mov_b32_e32 v16, v13
	v_mov_b32_e32 v13, v15
	v_mov_b32_e32 v17, v14
	v_pk_mul_f32 v[12:13], v[12:13], v[112:113]
	ds_bpermute_b32 v21, v115, v20
	v_pk_fma_f32 v[12:13], v[16:17], v[108:109], v[12:13]
	s_waitcnt lgkmcnt(2)
	v_add_f32_e32 v14, v18, v19
	v_add_f32_e32 v12, v12, v13
	ds_bpermute_b32 v13, v114, v12
	ds_bpermute_b32 v15, v116, v14
	s_waitcnt lgkmcnt(2)
	v_add_f32_e32 v16, v20, v21
	ds_bpermute_b32 v17, v116, v16
	v_add_f32_e32 v73, v53, v55
	s_waitcnt lgkmcnt(2)
	v_add_f32_e32 v12, v12, v13
	ds_bpermute_b32 v13, v115, v12
	s_waitcnt lgkmcnt(2)
	v_add_f32_e32 v65, v14, v15
	s_waitcnt lgkmcnt(1)
	v_add_f32_e32 v74, v16, v17
	ds_bpermute_b32 v75, v117, v74
	ds_bpermute_b32 v67, v117, v65
	s_waitcnt lgkmcnt(2)
	v_add_f32_e32 v82, v12, v13
	v_add_co_u32_e32 v12, vcc, s17, v48
	ds_bpermute_b32 v83, v116, v82
	s_nop 0
	v_addc_co_u32_e32 v13, vcc, 0, v49, vcc
	v_add_co_u32_e32 v14, vcc, s91, v48
	s_waitcnt lgkmcnt(0)
	v_add_f32_e32 v53, v82, v83
	v_addc_co_u32_e32 v15, vcc, 0, v49, vcc
	v_add_co_u32_e32 v16, vcc, s50, v48
	global_load_dwordx4 v[94:97], v[14:15], off offset:-4096
	global_load_dwordx4 v[132:135], v[14:15], off
	v_addc_co_u32_e32 v17, vcc, 0, v49, vcc
	v_add_co_u32_e32 v18, vcc, s90, v48
	ds_bpermute_b32 v55, v117, v53
	s_nop 0
	v_addc_co_u32_e32 v19, vcc, 0, v49, vcc
	global_load_dwordx4 v[136:139], v[14:15], off offset:2048
	global_load_dwordx4 v[140:143], v[18:19], off offset:-4096
	global_load_dwordx4 v[144:147], v[12:13], off offset:2048
	global_load_dwordx4 v[44:47], v[16:17], off offset:2048
	global_load_dwordx4 v[40:43], v[18:19], off
	global_load_dwordx4 v[32:35], v[18:19], off offset:2048
	v_add_co_u32_e32 v12, vcc, s96, v48
	v_add_f32_e32 v72, v65, v67
	s_nop 0
	v_addc_co_u32_e32 v13, vcc, 0, v49, vcc
	v_add_co_u32_e32 v14, vcc, s1, v48
	s_nop 1
	v_addc_co_u32_e32 v15, vcc, 0, v49, vcc
	v_add_co_u32_e32 v70, vcc, s51, v48
	global_load_dwordx4 v[36:39], v[14:15], off offset:-4096
	global_load_dwordx4 v[24:27], v[14:15], off
	v_addc_co_u32_e32 v71, vcc, 0, v49, vcc
	v_add_co_u32_e32 v50, vcc, s92, v48
	s_nop 1
	v_addc_co_u32_e32 v51, vcc, 0, v49, vcc
	global_load_dwordx4 v[20:23], v[14:15], off offset:2048
	global_load_dwordx4 v[16:19], v[50:51], off offset:-4096
	global_load_dwordx4 v[28:31], v[12:13], off offset:2048
	s_nop 0
	global_load_dwordx4 v[12:15], v[70:71], off offset:2048
	v_add_f32_e32 v70, v74, v75
	v_mov_b32_e32 v74, v9
	v_mov_b32_e32 v9, v11
	v_mov_b32_e32 v75, v10
	v_pk_mul_f32 v[8:9], v[8:9], v[112:113]
	s_waitcnt lgkmcnt(0)
	v_add_f32_e32 v71, v53, v55
	v_pk_fma_f32 v[8:9], v[74:75], v[108:109], v[8:9]
	s_nop 0
	v_add_f32_e32 v10, v8, v9
	s_waitcnt vmcnt(16)
	v_mov_b32_e32 v8, v5
	v_mov_b32_e32 v9, v6
	v_mov_b32_e32 v5, v7
	v_mul_f32_e32 v6, v108, v123
	v_mul_f32_e32 v7, v113, v124
	v_pk_mul_f32 v[4:5], v[4:5], v[112:113]
	v_fmac_f32_e32 v6, v112, v121
	v_fmac_f32_e32 v7, v109, v122
	v_pk_fma_f32 v[4:5], v[8:9], v[108:109], v[4:5]
	v_add_f32_e32 v6, v6, v7
	v_add_f32_e32 v4, v4, v5
	ds_bpermute_b32 v7, v114, v6
	ds_bpermute_b32 v5, v114, v4
	ds_bpermute_b32 v11, v114, v10
	s_waitcnt lgkmcnt(2)
	v_add_f32_e32 v6, v6, v7
	s_waitcnt lgkmcnt(1)
	v_add_f32_e32 v4, v4, v5
	ds_bpermute_b32 v7, v115, v6
	ds_bpermute_b32 v5, v115, v4
	s_waitcnt lgkmcnt(2)
	v_add_f32_e32 v8, v10, v11
	ds_bpermute_b32 v9, v115, v8
	s_waitcnt lgkmcnt(2)
	v_add_f32_e32 v6, v6, v7
	s_waitcnt lgkmcnt(1)
	v_add_f32_e32 v4, v4, v5
	ds_bpermute_b32 v7, v116, v6
	ds_bpermute_b32 v5, v116, v4
	s_waitcnt lgkmcnt(2)
	v_add_f32_e32 v8, v8, v9
	ds_bpermute_b32 v9, v116, v8
	s_waitcnt lgkmcnt(2)
	v_add_f32_e32 v6, v6, v7
	s_waitcnt lgkmcnt(1)
	v_add_f32_e32 v4, v4, v5
	ds_bpermute_b32 v7, v117, v6
	ds_bpermute_b32 v5, v117, v4
	s_waitcnt lgkmcnt(2)
	v_add_f32_e32 v8, v8, v9
	ds_bpermute_b32 v9, v117, v8
	s_waitcnt lgkmcnt(2)
	v_add_f32_e32 v53, v6, v7
	s_waitcnt lgkmcnt(1)
	v_add_f32_e32 v65, v4, v5
	v_cndmask_b32_e64 v4, v130, v237, s[38:39]
	v_max_f32_e32 v5, v53, v120
	v_max3_f32 v5, v5, v4, v126
	v_max3_f32 v5, v5, v128, v125
	v_max3_f32 v5, v5, v129, v127
	v_max3_f32 v5, v5, v93, v92
	v_max3_f32 v5, v5, v85, v84
	v_max3_f32 v5, v5, v77, v76
	v_max3_f32 v5, v5, v69, v68
	v_max3_f32 v5, v5, v66, v64
	v_max3_f32 v5, v5, v62, v58
	v_max3_f32 v5, v5, v61, v57
	v_max3_f32 v5, v5, v60, v56
	v_max3_f32 v5, v5, v63, v59
	v_max3_f32 v5, v5, v54, v52
	v_max3_f32 v5, v5, v73, v72
	s_waitcnt lgkmcnt(0)
	v_add_f32_e32 v67, v8, v9
	v_max3_f32 v5, v5, v70, v71
	v_max3_f32 v5, v5, v67, v65
	ds_bpermute_b32 v6, v118, v5
	s_waitcnt lgkmcnt(0)
	v_max_f32_e32 v6, v6, v6
	v_max_f32_e32 v5, v5, v6
	ds_bpermute_b32 v6, v119, v5
	s_waitcnt lgkmcnt(0)
	v_max_f32_e32 v6, v6, v6
	v_max_f32_e32 v55, v5, v6
	v_sub_f32_e32 v4, v4, v55
	v_exp_f32_e32 v4, v4
	v_sub_f32_e32 v8, v126, v55
	v_exp_f32_e32 v8, v8
	v_add_f32_e32 v9, 0, v4
	s_waitcnt vmcnt(15)
	v_pk_fma_f32 v[6:7], v[78:79], v[4:5], 0 op_sel_hi:[1,0,0]
	v_pk_fma_f32 v[4:5], v[80:81], v[4:5], 0 op_sel_hi:[1,0,0]
	v_add_f32_e32 v9, v8, v9
	s_waitcnt vmcnt(14)
	v_pk_fma_f32 v[4:5], v[88:89], v[8:9], v[4:5] op_sel_hi:[1,0,1]
	v_pk_fma_f32 v[6:7], v[86:87], v[8:9], v[6:7] op_sel_hi:[1,0,1]
	v_sub_f32_e32 v8, v128, v55
	v_exp_f32_e32 v8, v8
	s_nop 0
	v_add_f32_e32 v9, v8, v9
	s_waitcnt vmcnt(13)
	v_pk_fma_f32 v[6:7], v[94:95], v[8:9], v[6:7] op_sel_hi:[1,0,1]
	v_pk_fma_f32 v[4:5], v[96:97], v[8:9], v[4:5] op_sel_hi:[1,0,1]
	v_sub_f32_e32 v8, v125, v55
	v_exp_f32_e32 v8, v8
	s_nop 0
	v_add_f32_e32 v9, v8, v9
	s_waitcnt vmcnt(9)
	v_pk_fma_f32 v[4:5], v[146:147], v[8:9], v[4:5] op_sel_hi:[1,0,1]
	v_pk_fma_f32 v[6:7], v[144:145], v[8:9], v[6:7] op_sel_hi:[1,0,1]
	v_sub_f32_e32 v8, v129, v55
	v_exp_f32_e32 v8, v8
	s_nop 0
	v_add_f32_e32 v9, v8, v9
	v_pk_fma_f32 v[6:7], v[132:133], v[8:9], v[6:7] op_sel_hi:[1,0,1]
	v_pk_fma_f32 v[4:5], v[134:135], v[8:9], v[4:5] op_sel_hi:[1,0,1]
	v_sub_f32_e32 v8, v127, v55
	v_exp_f32_e32 v8, v8
	s_nop 0
	v_add_f32_e32 v9, v8, v9
	v_pk_fma_f32 v[4:5], v[138:139], v[8:9], v[4:5] op_sel_hi:[1,0,1]
	v_pk_fma_f32 v[6:7], v[136:137], v[8:9], v[6:7] op_sel_hi:[1,0,1]
	v_sub_f32_e32 v8, v93, v55
	v_exp_f32_e32 v8, v8
	s_nop 0
	v_add_f32_e32 v9, v8, v9
	v_pk_fma_f32 v[6:7], v[140:141], v[8:9], v[6:7] op_sel_hi:[1,0,1]
	v_pk_fma_f32 v[4:5], v[142:143], v[8:9], v[4:5] op_sel_hi:[1,0,1]
	v_sub_f32_e32 v8, v92, v55
	v_exp_f32_e32 v8, v8
	s_nop 0
	v_add_f32_e32 v9, v8, v9
	s_waitcnt vmcnt(8)
	v_pk_fma_f32 v[4:5], v[46:47], v[8:9], v[4:5] op_sel_hi:[1,0,1]
	v_pk_fma_f32 v[6:7], v[44:45], v[8:9], v[6:7] op_sel_hi:[1,0,1]
	v_sub_f32_e32 v8, v85, v55
	v_exp_f32_e32 v8, v8
	s_nop 0
	v_add_f32_e32 v9, v8, v9
	s_waitcnt vmcnt(7)
	v_pk_fma_f32 v[6:7], v[40:41], v[8:9], v[6:7] op_sel_hi:[1,0,1]
	v_pk_fma_f32 v[4:5], v[42:43], v[8:9], v[4:5] op_sel_hi:[1,0,1]
	v_sub_f32_e32 v8, v84, v55
	v_exp_f32_e32 v8, v8
	s_nop 0
	v_add_f32_e32 v9, v8, v9
	s_waitcnt vmcnt(6)
	v_pk_fma_f32 v[4:5], v[34:35], v[8:9], v[4:5] op_sel_hi:[1,0,1]
	v_pk_fma_f32 v[6:7], v[32:33], v[8:9], v[6:7] op_sel_hi:[1,0,1]
	v_sub_f32_e32 v8, v77, v55
	v_exp_f32_e32 v8, v8
	s_nop 0
	v_add_f32_e32 v9, v8, v9
	s_waitcnt vmcnt(5)
	v_pk_fma_f32 v[6:7], v[36:37], v[8:9], v[6:7] op_sel_hi:[1,0,1]
	v_pk_fma_f32 v[4:5], v[38:39], v[8:9], v[4:5] op_sel_hi:[1,0,1]
	v_sub_f32_e32 v8, v76, v55
	v_exp_f32_e32 v8, v8
	s_nop 0
	v_add_f32_e32 v9, v8, v9
	s_waitcnt vmcnt(1)
	v_pk_fma_f32 v[4:5], v[30:31], v[8:9], v[4:5] op_sel_hi:[1,0,1]
	v_pk_fma_f32 v[6:7], v[28:29], v[8:9], v[6:7] op_sel_hi:[1,0,1]
	v_sub_f32_e32 v8, v69, v55
	v_exp_f32_e32 v8, v8
	s_nop 0
	v_add_f32_e32 v9, v8, v9
	v_pk_fma_f32 v[6:7], v[24:25], v[8:9], v[6:7] op_sel_hi:[1,0,1]
	v_pk_fma_f32 v[4:5], v[26:27], v[8:9], v[4:5] op_sel_hi:[1,0,1]
	v_sub_f32_e32 v8, v68, v55
	v_exp_f32_e32 v8, v8
	s_nop 0
	v_add_f32_e32 v9, v8, v9
	v_pk_fma_f32 v[4:5], v[22:23], v[8:9], v[4:5] op_sel_hi:[1,0,1]
	v_pk_fma_f32 v[6:7], v[20:21], v[8:9], v[6:7] op_sel_hi:[1,0,1]
	v_sub_f32_e32 v8, v66, v55
	v_exp_f32_e32 v8, v8
	s_nop 0
	v_add_f32_e32 v9, v8, v9
	v_pk_fma_f32 v[6:7], v[16:17], v[8:9], v[6:7] op_sel_hi:[1,0,1]
	v_pk_fma_f32 v[4:5], v[18:19], v[8:9], v[4:5] op_sel_hi:[1,0,1]
	v_sub_f32_e32 v8, v64, v55
	v_exp_f32_e32 v8, v8
	s_nop 0
	v_add_f32_e32 v64, v8, v9
	s_waitcnt vmcnt(0)
	v_pk_fma_f32 v[68:69], v[14:15], v[8:9], v[4:5] op_sel_hi:[1,0,1]
	v_pk_fma_f32 v[90:91], v[12:13], v[8:9], v[6:7] op_sel_hi:[1,0,1]
	v_add_co_u32_e32 v4, vcc, s56, v48
	s_nop 1
	v_addc_co_u32_e32 v5, vcc, 0, v49, vcc
	v_add_co_u32_e32 v6, vcc, s93, v48
	s_nop 1
	v_addc_co_u32_e32 v7, vcc, 0, v49, vcc
	global_load_dwordx4 v[28:31], v[50:51], off offset:2048
	global_load_dwordx4 v[32:35], v[6:7], off offset:-4096
	global_load_dwordx4 v[36:39], v[6:7], off
	global_load_dwordx4 v[40:43], v[6:7], off offset:2048
	v_add_co_u32_e32 v6, vcc, s57, v48
	s_nop 1
	v_addc_co_u32_e32 v7, vcc, 0, v49, vcc
	v_add_co_u32_e32 v8, vcc, s6, v48
	s_nop 1
	v_addc_co_u32_e32 v9, vcc, 0, v49, vcc
	global_load_dwordx4 v[44:47], v[4:5], off offset:2048
	global_load_dwordx4 v[74:77], v[6:7], off offset:2048
	global_load_dwordx4 v[78:81], v[8:9], off offset:-4096
	global_load_dwordx4 v[82:85], v[8:9], off
	v_add_co_u32_e32 v4, vcc, s58, v48
	s_nop 1
	v_addc_co_u32_e32 v5, vcc, 0, v49, vcc
	v_add_co_u32_e32 v6, vcc, s95, v48
	s_nop 1
	v_addc_co_u32_e32 v7, vcc, 0, v49, vcc
	global_load_dwordx4 v[86:89], v[8:9], off offset:2048
	global_load_dwordx4 v[24:27], v[6:7], off offset:-4096
	global_load_dwordx4 v[16:19], v[6:7], off
	global_load_dwordx4 v[12:15], v[6:7], off offset:2048
	v_add_co_u32_e32 v6, vcc, s52, v48
	s_nop 1
	v_addc_co_u32_e32 v7, vcc, 0, v49, vcc
	global_load_dwordx4 v[20:23], v[4:5], off offset:2048
	global_load_dwordx4 v[8:11], v[6:7], off
	s_nop 0
	global_load_dwordx4 v[48:51], v[50:51], off
	s_nop 0
	global_load_dwordx4 v[4:7], v[6:7], off offset:2048
	v_sub_f32_e32 v62, v62, v55
	v_exp_f32_e32 v62, v62
	v_sub_f32_e32 v58, v58, v55
	v_exp_f32_e32 v58, v58
	s_waitcnt vmcnt(1)
	v_pk_fma_f32 v[48:49], v[48:49], v[62:63], v[90:91] op_sel_hi:[1,0,1]
	v_add_f32_e32 v64, v62, v64
	v_pk_fma_f32 v[28:29], v[28:29], v[58:59], v[48:49] op_sel_hi:[1,0,1]
	v_sub_f32_e32 v48, v61, v55
	v_exp_f32_e32 v48, v48
	v_pk_fma_f32 v[50:51], v[50:51], v[62:63], v[68:69] op_sel_hi:[1,0,1]
	v_add_f32_e32 v62, v58, v64
	v_pk_fma_f32 v[30:31], v[30:31], v[58:59], v[50:51] op_sel_hi:[1,0,1]
	v_add_f32_e32 v49, v48, v62
	v_pk_fma_f32 v[28:29], v[32:33], v[48:49], v[28:29] op_sel_hi:[1,0,1]
	v_sub_f32_e32 v32, v57, v55
	v_exp_f32_e32 v32, v32
	v_pk_fma_f32 v[30:31], v[34:35], v[48:49], v[30:31] op_sel_hi:[1,0,1]
	v_add_f32_e32 v33, v32, v49
	v_pk_fma_f32 v[30:31], v[46:47], v[32:33], v[30:31] op_sel_hi:[1,0,1]
	v_pk_fma_f32 v[28:29], v[44:45], v[32:33], v[28:29] op_sel_hi:[1,0,1]
	v_sub_f32_e32 v32, v60, v55
	v_exp_f32_e32 v32, v32
	s_nop 0
	v_add_f32_e32 v33, v32, v33
	v_pk_fma_f32 v[28:29], v[36:37], v[32:33], v[28:29] op_sel_hi:[1,0,1]
	v_pk_fma_f32 v[30:31], v[38:39], v[32:33], v[30:31] op_sel_hi:[1,0,1]
	v_sub_f32_e32 v32, v56, v55
	v_exp_f32_e32 v32, v32
	s_nop 0
	v_add_f32_e32 v33, v32, v33
	v_pk_fma_f32 v[30:31], v[42:43], v[32:33], v[30:31] op_sel_hi:[1,0,1]
	v_pk_fma_f32 v[28:29], v[40:41], v[32:33], v[28:29] op_sel_hi:[1,0,1]
	v_sub_f32_e32 v32, v63, v55
	v_exp_f32_e32 v32, v32
	s_nop 0
	v_add_f32_e32 v33, v32, v33
	v_pk_fma_f32 v[28:29], v[78:79], v[32:33], v[28:29] op_sel_hi:[1,0,1]
	v_pk_fma_f32 v[30:31], v[80:81], v[32:33], v[30:31] op_sel_hi:[1,0,1]
	v_sub_f32_e32 v32, v59, v55
	v_exp_f32_e32 v32, v32
	s_nop 0
	v_add_f32_e32 v33, v32, v33
	v_pk_fma_f32 v[30:31], v[76:77], v[32:33], v[30:31] op_sel_hi:[1,0,1]
	v_pk_fma_f32 v[28:29], v[74:75], v[32:33], v[28:29] op_sel_hi:[1,0,1]
	v_sub_f32_e32 v32, v54, v55
	v_exp_f32_e32 v32, v32
	s_nop 0
	v_add_f32_e32 v33, v32, v33
	v_pk_fma_f32 v[28:29], v[82:83], v[32:33], v[28:29] op_sel_hi:[1,0,1]
	v_pk_fma_f32 v[30:31], v[84:85], v[32:33], v[30:31] op_sel_hi:[1,0,1]
	v_sub_f32_e32 v32, v52, v55
	v_exp_f32_e32 v32, v32
	s_nop 0
	v_add_f32_e32 v33, v32, v33
	v_pk_fma_f32 v[30:31], v[88:89], v[32:33], v[30:31] op_sel_hi:[1,0,1]
	v_pk_fma_f32 v[28:29], v[86:87], v[32:33], v[28:29] op_sel_hi:[1,0,1]
	v_sub_f32_e32 v32, v73, v55
	v_exp_f32_e32 v32, v32
	s_nop 0
	v_add_f32_e32 v33, v32, v33
	v_pk_fma_f32 v[24:25], v[24:25], v[32:33], v[28:29] op_sel_hi:[1,0,1]
	v_sub_f32_e32 v28, v72, v55
	v_exp_f32_e32 v28, v28
	v_pk_fma_f32 v[26:27], v[26:27], v[32:33], v[30:31] op_sel_hi:[1,0,1]
	v_add_f32_e32 v29, v28, v33
	v_pk_fma_f32 v[20:21], v[20:21], v[28:29], v[24:25] op_sel_hi:[1,0,1]
	v_sub_f32_e32 v24, v70, v55
	v_exp_f32_e32 v24, v24
	v_pk_fma_f32 v[22:23], v[22:23], v[28:29], v[26:27] op_sel_hi:[1,0,1]
	v_add_f32_e32 v25, v24, v29
	v_pk_fma_f32 v[16:17], v[16:17], v[24:25], v[20:21] op_sel_hi:[1,0,1]
	v_sub_f32_e32 v20, v71, v55
	v_exp_f32_e32 v20, v20
	v_pk_fma_f32 v[18:19], v[18:19], v[24:25], v[22:23] op_sel_hi:[1,0,1]
	v_add_f32_e32 v21, v20, v25
	v_pk_fma_f32 v[12:13], v[12:13], v[20:21], v[16:17] op_sel_hi:[1,0,1]
	v_sub_f32_e32 v16, v67, v55
	v_exp_f32_e32 v16, v16
	v_pk_fma_f32 v[14:15], v[14:15], v[20:21], v[18:19] op_sel_hi:[1,0,1]
	v_add_f32_e32 v17, v16, v21
	v_pk_fma_f32 v[8:9], v[8:9], v[16:17], v[12:13] op_sel_hi:[1,0,1]
	v_sub_f32_e32 v12, v65, v55
	v_exp_f32_e32 v12, v12
	v_pk_fma_f32 v[10:11], v[10:11], v[16:17], v[14:15] op_sel_hi:[1,0,1]
	v_add_f32_e32 v13, v12, v17
	s_waitcnt vmcnt(0)
	v_pk_fma_f32 v[10:11], v[6:7], v[12:13], v[10:11] op_sel_hi:[1,0,1]
	v_pk_fma_f32 v[4:5], v[4:5], v[12:13], v[8:9] op_sel_hi:[1,0,1]
	ds_bpermute_b32 v12, v118, v13
	ds_bpermute_b32 v6, v118, v4
	ds_bpermute_b32 v7, v118, v5
	ds_bpermute_b32 v8, v118, v10
	ds_bpermute_b32 v9, v118, v11
	s_waitcnt lgkmcnt(4)
	v_add_f32_e32 v12, v13, v12
	ds_bpermute_b32 v13, v119, v12
	s_waitcnt lgkmcnt(3)
	v_pk_add_f32 v[4:5], v[4:5], v[6:7]
	ds_bpermute_b32 v6, v119, v4
	s_waitcnt lgkmcnt(2)
	v_pk_add_f32 v[8:9], v[10:11], v[8:9]
	ds_bpermute_b32 v7, v119, v5
	ds_bpermute_b32 v10, v119, v8
	ds_bpermute_b32 v11, v119, v9
	s_and_saveexec_b64 s[30:31], s[38:39]
	s_cbranch_execz .LBB0_630
	global_load_dwordx2 v[14:15], v2, s[22:23] offset:2048
	s_waitcnt lgkmcnt(2)
	v_pk_add_f32 v[4:5], v[4:5], v[6:7]
	s_waitcnt lgkmcnt(0)
	v_pk_add_f32 v[6:7], v[8:9], v[10:11]
	v_sub_f32_e32 v8, v53, v55
	v_sub_f32_e32 v9, v120, v55
	v_exp_f32_e32 v8, v8
	v_exp_f32_e32 v9, v9
	v_add_f32_e32 v12, v12, v13
	v_lshlrev_b32_e32 v18, 16, v107
	v_and_b32_e32 v19, 0xffff0000, v107
	v_add_f32_e32 v10, v8, v12
	v_pk_fma_f32 v[6:7], v[8:9], v[18:19], v[6:7] op_sel_hi:[0,1,1]
	v_add_f32_e32 v9, v9, v10
	s_mul_hi_i32 s1, s20, 0xc00
	s_mul_i32 s4, s20, 0xc00
	v_div_scale_f32 v10, s[20:21], v9, v9, 1.0
	v_rcp_f32_e32 v11, v10
	v_lshlrev_b32_e32 v16, 16, v106
	v_and_b32_e32 v17, 0xffff0000, v106
	v_pk_fma_f32 v[4:5], v[8:9], v[16:17], v[4:5] op_sel_hi:[0,1,1]
	v_fma_f32 v12, -v10, v11, 1.0
	v_div_scale_f32 v8, vcc, 1.0, v9, 1.0
	v_fmac_f32_e32 v11, v12, v11
	v_mul_f32_e32 v12, v8, v11
	v_fma_f32 v13, -v10, v12, v8
	v_fmac_f32_e32 v12, v13, v11
	v_fma_f32 v8, -v10, v12, v8
	s_lshl_b32 s0, s0, 6
	v_div_fmas_f32 v8, v8, v11, v12
	s_add_u32 s4, s81, s4
	v_div_fixup_f32 v8, v8, v9, 1.0
	s_addc_u32 s1, s9, s1
	s_lshl_b32 s0, s0, 1
	v_mul_f32_e32 v4, v8, v4
	v_mul_f32_e32 v5, v8, v5
	v_mul_f32_e32 v6, v8, v6
	v_mul_f32_e32 v7, v8, v7
	s_add_u32 s0, s4, s0
	s_addc_u32 s1, s1, 0
	s_waitcnt vmcnt(0)
	v_lshlrev_b32_e32 v8, 16, v14
	v_and_b32_e32 v9, 0xffff0000, v14
	v_lshlrev_b32_e32 v10, 16, v15
	v_and_b32_e32 v11, 0xffff0000, v15
	v_mul_f32_e32 v4, v4, v8
	v_mul_f32_e32 v5, v5, v9
	v_mul_f32_e32 v6, v6, v10
	v_mul_f32_e32 v7, v7, v11
	v_cvt_pk_bf16_f32 v4, v4, v5
	v_cvt_pk_bf16_f32 v5, v6, v7
	global_store_dwordx2 v2, v[4:5], s[0:1] sc1
	s_branch .LBB0_630
